# loop-edge edit: K-loop counter/pointer/exit-test SALU hoisted above the loop-back barrier in all six GEMM loops
# baseline (speedup 1.0000x reference)
; #define PG8_STAGE(bufoff, gbase, voff) do { _Pragma("unroll") for (int _i = 0; _i < 2; ++_i) \
;         __builtin_amdgcn_global_load_lds((const unsigned*)((const char*)(gbase) + (voff)[_i]), (PG8_LAS unsigned*)(lds + (bufoff) + ldsw + _i * 8192), 16, 0, 0); } while (0)
; #define PG8_LDA(dst, b, h) do { _Pragma("unroll") for (int m = 0; m < 4; ++m) _Pragma("unroll") for (int k = 0; k < 2; ++k) dst[m][k] = *(const PG8_LAS bf16x8*)(lds + PG8_SA(b, h) + aoff + m * 2048 + k * 1024); } while (0)
; #define PG8_LDB(dst, b, h) do { _Pragma("unroll") for (int n = 0; n < 2; ++n) _Pragma("unroll") for (int k = 0; k < 2; ++k) dst[n][k] = *(const PG8_LAS bf16x8*)(lds + PG8_SB(b, h) + boff + n * 2048 + k * 1024); } while (0)
; #define PG8_MMA(ai, bj, At, Bt) do { __builtin_amdgcn_s_setprio(1); _Pragma("unroll") for (int m = 0; m < 4; ++m) _Pragma("unroll") for (int n = 0; n < 2; ++n) _Pragma("unroll") for (int k = 0; k < 2; ++k) \
;         acc[ai][bj][m][n] = __builtin_amdgcn_mfma_f32_16x16x32_bf16(Bt[n][k], At[m][k], acc[ai][bj][m][n], 0, 0, 0); __builtin_amdgcn_s_setprio(0); } while (0)
; #define PG8_WAIT_V(n) asm volatile("s_waitcnt vmcnt(" #n ")" ::: "memory")
; #define PG8_WAIT_L(n) asm volatile("s_waitcnt lgkmcnt(" #n ")" ::: "memory")
; #define PG8_BAR __builtin_amdgcn_s_barrier()
; #define PG8_SCHED __builtin_amdgcn_sched_barrier(0)
; template <class Epi, class Sched, bool ALIGN_EPI = false, bool SP2 = false>
; __device__ __forceinline__ void gemm_phase(PG8_LAS unsigned char* lds, const Gemm g, const Sched& S, const Epi& E) {
;     ...
;         for (int t = 0; t < nt; t += 2) {
;             const bool last = (t == nt - 2);
;             const char* a1 = cA + (size_t)(t + 1) * kstep;
;             const char* a2 = last ? nA : cA + (size_t)(t + 2) * kstep; const char* b2 = last ? nB : cB + (size_t)(t + 2) * kstep;
;             const char* a3 = a2 + kstep; const char* b3 = b2 + kstep;
;             if (last && has_next) S.a_ready(nxt);
;             if constexpr (SP2) {
;             PG8_LDB(B0, 0, 0); PG8_LDB(B1, 0, 1); PG8_SCHED; PG8_LDA(At, 0, 0); PG8_STAGE(PG8_SA(1, 1), a1 + hstep, voffA);
;             PG8_WAIT_V(8); PG8_WAIT_L(0); PG8_BAR; PG8_MMA(0, 0, At, B0); PG8_MMA(0, 1, At, B1); PG8_BAR; PG8_SCHED;
;             PG8_LDA(At, 0, 1); PG8_STAGE(PG8_SB(0, 0), b2, voffB); PG8_STAGE(PG8_SB(0, 1), b2 + hstep, voffB); PG8_STAGE(PG8_SA(0, 0), a2, voffA);
.LBB0_292:
	ds_read_b128 v[154:157], v150
	ds_read_b128 v[158:161], v150 offset:1024
	ds_read_b128 v[162:165], v150 offset:2048
	ds_read_b128 v[166:169], v150 offset:3072
	ds_read_b128 v[170:173], v151
	ds_read_b128 v[174:177], v151 offset:1024
	ds_read_b128 v[178:181], v151 offset:2048
	ds_read_b128 v[182:185], v151 offset:3072
	s_add_u32 s38, s36, 0xfffc0080
	s_addc_u32 s39, s37, -1
	s_cmp_eq_u32 s67, 12
	s_cselect_b32 s41, s27, s39
	s_cselect_b32 s40, s63, s38
	s_cselect_b32 s39, s25, s66
	s_cselect_b32 s38, s64, s65
	v_lshl_add_u64 v[218:219], s[36:37], 0, v[138:139]
	s_add_i32 m0, s35, 0xc000
	ds_read_b128 v[186:189], v152
	ds_read_b128 v[190:193], v152 offset:1024
	ds_read_b128 v[194:197], v152 offset:2048
	ds_read_b128 v[198:201], v152 offset:3072
	ds_read_b128 v[202:205], v152 offset:4096
	ds_read_b128 v[206:209], v152 offset:5120
	ds_read_b128 v[210:213], v152 offset:6144
	ds_read_b128 v[214:217], v152 offset:7168
	global_load_lds_dwordx4 v[218:219], off
	v_lshl_add_u64 v[218:219], s[36:37], 0, v[140:141]
	s_add_i32 m0, s35, 0xe000
	s_nop 0
	global_load_lds_dwordx4 v[218:219], off
	s_waitcnt vmcnt(8)
	s_waitcnt lgkmcnt(0)
	s_barrier
	s_setprio 1
	s_waitcnt lgkmcnt(0)
	v_mfma_f32_16x16x32_bf16 v[126:129], v[154:157], v[186:189], v[126:129]
	v_mfma_f32_16x16x32_bf16 v[122:125], v[162:165], v[186:189], v[122:125]
	v_mfma_f32_16x16x32_bf16 v[110:113], v[154:157], v[194:197], v[110:113]
	v_mfma_f32_16x16x32_bf16 v[106:109], v[162:165], v[194:197], v[106:109]
	v_mfma_f32_16x16x32_bf16 v[94:97], v[154:157], v[202:205], v[94:97]
	v_mfma_f32_16x16x32_bf16 v[90:93], v[162:165], v[202:205], v[90:93]
	v_mfma_f32_16x16x32_bf16 v[78:81], v[154:157], v[210:213], v[78:81]
	v_mfma_f32_16x16x32_bf16 v[74:77], v[162:165], v[210:213], v[74:77]
	v_mfma_f32_16x16x32_bf16 v[126:129], v[158:161], v[190:193], v[126:129]
	v_mfma_f32_16x16x32_bf16 v[122:125], v[166:169], v[190:193], v[122:125]
	v_mfma_f32_16x16x32_bf16 v[110:113], v[158:161], v[198:201], v[110:113]
	v_mfma_f32_16x16x32_bf16 v[106:109], v[166:169], v[198:201], v[106:109]
	v_mfma_f32_16x16x32_bf16 v[94:97], v[158:161], v[206:209], v[94:97]
	v_mfma_f32_16x16x32_bf16 v[90:93], v[166:169], v[206:209], v[90:93]
	v_mfma_f32_16x16x32_bf16 v[78:81], v[158:161], v[214:217], v[78:81]
	v_mfma_f32_16x16x32_bf16 v[74:77], v[166:169], v[214:217], v[74:77]
	s_setprio 0
	s_setprio 1
	v_mfma_f32_16x16x32_bf16 v[118:121], v[170:173], v[186:189], v[118:121]
	v_mfma_f32_16x16x32_bf16 v[114:117], v[178:181], v[186:189], v[114:117]
	v_mfma_f32_16x16x32_bf16 v[102:105], v[170:173], v[194:197], v[102:105]
	v_mfma_f32_16x16x32_bf16 v[98:101], v[178:181], v[194:197], v[98:101]
	v_mfma_f32_16x16x32_bf16 v[86:89], v[170:173], v[202:205], v[86:89]
	v_mfma_f32_16x16x32_bf16 v[82:85], v[178:181], v[202:205], v[82:85]
	v_mfma_f32_16x16x32_bf16 v[70:73], v[170:173], v[210:213], v[70:73]
	v_mfma_f32_16x16x32_bf16 v[66:69], v[178:181], v[210:213], v[66:69]
	v_mfma_f32_16x16x32_bf16 v[118:121], v[174:177], v[190:193], v[118:121]
	v_mfma_f32_16x16x32_bf16 v[114:117], v[182:185], v[190:193], v[114:117]
	v_mfma_f32_16x16x32_bf16 v[102:105], v[174:177], v[198:201], v[102:105]
	v_mfma_f32_16x16x32_bf16 v[98:101], v[182:185], v[198:201], v[98:101]
	v_mfma_f32_16x16x32_bf16 v[86:89], v[174:177], v[206:209], v[86:89]
	v_mfma_f32_16x16x32_bf16 v[82:85], v[182:185], v[206:209], v[82:85]
	v_mfma_f32_16x16x32_bf16 v[70:73], v[174:177], v[214:217], v[70:73]
	v_mfma_f32_16x16x32_bf16 v[66:69], v[182:185], v[214:217], v[66:69]
	s_setprio 0
	s_barrier
	s_add_i32 s70, s55, s42
	v_lshl_add_u64 v[218:219], s[38:39], 0, v[134:135]
	s_mov_b32 m0, s70
	ds_read_b128 v[186:189], v152 offset:16384
	ds_read_b128 v[190:193], v152 offset:17408
	ds_read_b128 v[194:197], v152 offset:18432
	ds_read_b128 v[198:201], v152 offset:19456
	ds_read_b128 v[202:205], v152 offset:20480
	ds_read_b128 v[206:209], v152 offset:21504
	ds_read_b128 v[210:213], v152 offset:22528
	ds_read_b128 v[214:217], v152 offset:23552
	global_load_lds_dwordx4 v[218:219], off
	s_add_i32 m0, s70, 0x2000
	s_add_u32 s70, s38, 0x40000
	v_lshl_add_u64 v[220:221], s[38:39], 0, v[130:131]
	s_addc_u32 s71, s39, 0
	s_add_i32 s74, s58, s42
	global_load_lds_dwordx4 v[220:221], off
	v_lshl_add_u64 v[222:223], s[70:71], 0, v[134:135]
	s_mov_b32 m0, s74
	v_lshl_add_u64 v[224:225], s[40:41], 0, v[132:133]
	global_load_lds_dwordx4 v[222:223], off
	v_lshl_add_u64 v[222:223], s[70:71], 0, v[130:131]
	s_add_i32 m0, s74, 0x2000
	s_nop 0
	global_load_lds_dwordx4 v[222:223], off
	v_lshl_add_u64 v[222:223], s[40:41], 0, v[136:137]
	s_mov_b32 m0, s35
	s_nop 0
	global_load_lds_dwordx4 v[222:223], off
	s_mov_b32 m0, s45
	s_nop 0
	global_load_lds_dwordx4 v[224:225], off
	s_waitcnt vmcnt(8)
	s_waitcnt lgkmcnt(0)
	s_barrier
; #define PG8_STAGE(bufoff, gbase, voff) do { _Pragma("unroll") for (int _i = 0; _i < 2; ++_i) \
;         __builtin_amdgcn_global_load_lds((const unsigned*)((const char*)(gbase) + (voff)[_i]), (PG8_LAS unsigned*)(lds + (bufoff) + ldsw + _i * 8192), 16, 0, 0); } while (0)
; #define PG8_LDA(dst, b, h) do { _Pragma("unroll") for (int m = 0; m < 4; ++m) _Pragma("unroll") for (int k = 0; k < 2; ++k) dst[m][k] = *(const PG8_LAS bf16x8*)(lds + PG8_SA(b, h) + aoff + m * 2048 + k * 1024); } while (0)
; #define PG8_LDB(dst, b, h) do { _Pragma("unroll") for (int n = 0; n < 2; ++n) _Pragma("unroll") for (int k = 0; k < 2; ++k) dst[n][k] = *(const PG8_LAS bf16x8*)(lds + PG8_SB(b, h) + boff + n * 2048 + k * 1024); } while (0)
; #define PG8_MMA(ai, bj, At, Bt) do { __builtin_amdgcn_s_setprio(1); _Pragma("unroll") for (int m = 0; m < 4; ++m) _Pragma("unroll") for (int n = 0; n < 2; ++n) _Pragma("unroll") for (int k = 0; k < 2; ++k) \
;         acc[ai][bj][m][n] = __builtin_amdgcn_mfma_f32_16x16x32_bf16(Bt[n][k], At[m][k], acc[ai][bj][m][n], 0, 0, 0); __builtin_amdgcn_s_setprio(0); } while (0)
; #define PG8_WAIT_V(n) asm volatile("s_waitcnt vmcnt(" #n ")" ::: "memory")
; #define PG8_WAIT_L(n) asm volatile("s_waitcnt lgkmcnt(" #n ")" ::: "memory")
; #define PG8_BAR __builtin_amdgcn_s_barrier()
; #define PG8_SCHED __builtin_amdgcn_sched_barrier(0)
; template <class Epi, class Sched, bool ALIGN_EPI = false, bool SP2 = false>
; __device__ __forceinline__ void gemm_phase(PG8_LAS unsigned char* lds, const Gemm g, const Sched& S, const Epi& E) {
;     ...
;             PG8_WAIT_V(8); PG8_WAIT_L(0); PG8_BAR; PG8_MMA(1, 0, At, B0); PG8_MMA(1, 1, At, B1); PG8_BAR; PG8_SCHED;
;             PG8_LDB(B0, 1, 0); PG8_LDB(B1, 1, 1); PG8_SCHED; PG8_LDA(At, 1, 0); PG8_STAGE(PG8_SA(0, 1), a2 + hstep, voffA);
;             PG8_WAIT_V(8); PG8_WAIT_L(0); PG8_BAR; PG8_MMA(0, 0, At, B0); PG8_MMA(0, 1, At, B1); PG8_BAR; PG8_SCHED;
;             PG8_LDA(At, 1, 1); PG8_STAGE(PG8_SB(1, 0), b3, voffB); PG8_STAGE(PG8_SB(1, 1), b3 + hstep, voffB); PG8_STAGE(PG8_SA(1, 0), a3, voffA);
	s_setprio 1
	s_waitcnt lgkmcnt(0)
	v_mfma_f32_16x16x32_bf16 v[62:65], v[154:157], v[186:189], v[62:65]
	v_mfma_f32_16x16x32_bf16 v[58:61], v[162:165], v[186:189], v[58:61]
	v_mfma_f32_16x16x32_bf16 v[46:49], v[154:157], v[194:197], v[46:49]
	v_mfma_f32_16x16x32_bf16 v[42:45], v[162:165], v[194:197], v[42:45]
	v_mfma_f32_16x16x32_bf16 v[30:33], v[154:157], v[202:205], v[30:33]
	v_mfma_f32_16x16x32_bf16 v[26:29], v[162:165], v[202:205], v[26:29]
	v_mfma_f32_16x16x32_bf16 v[14:17], v[154:157], v[210:213], v[14:17]
	v_mfma_f32_16x16x32_bf16 v[10:13], v[162:165], v[210:213], v[10:13]
	v_mfma_f32_16x16x32_bf16 v[62:65], v[158:161], v[190:193], v[62:65]
	v_mfma_f32_16x16x32_bf16 v[58:61], v[166:169], v[190:193], v[58:61]
	v_mfma_f32_16x16x32_bf16 v[46:49], v[158:161], v[198:201], v[46:49]
	v_mfma_f32_16x16x32_bf16 v[42:45], v[166:169], v[198:201], v[42:45]
	v_mfma_f32_16x16x32_bf16 v[30:33], v[158:161], v[206:209], v[30:33]
	v_mfma_f32_16x16x32_bf16 v[26:29], v[166:169], v[206:209], v[26:29]
	v_mfma_f32_16x16x32_bf16 v[14:17], v[158:161], v[214:217], v[14:17]
	v_mfma_f32_16x16x32_bf16 v[10:13], v[166:169], v[214:217], v[10:13]
	s_setprio 0
	s_setprio 1
	v_mfma_f32_16x16x32_bf16 v[54:57], v[170:173], v[186:189], v[54:57]
	v_mfma_f32_16x16x32_bf16 v[50:53], v[178:181], v[186:189], v[50:53]
	v_mfma_f32_16x16x32_bf16 v[38:41], v[170:173], v[194:197], v[38:41]
	v_mfma_f32_16x16x32_bf16 v[34:37], v[178:181], v[194:197], v[34:37]
	v_mfma_f32_16x16x32_bf16 v[22:25], v[170:173], v[202:205], v[22:25]
	v_mfma_f32_16x16x32_bf16 v[18:21], v[178:181], v[202:205], v[18:21]
	v_mfma_f32_16x16x32_bf16 v[6:9], v[170:173], v[210:213], v[6:9]
	v_mfma_f32_16x16x32_bf16 v[2:5], v[178:181], v[210:213], v[2:5]
	v_mfma_f32_16x16x32_bf16 v[54:57], v[174:177], v[190:193], v[54:57]
	v_mfma_f32_16x16x32_bf16 v[50:53], v[182:185], v[190:193], v[50:53]
	v_mfma_f32_16x16x32_bf16 v[38:41], v[174:177], v[198:201], v[38:41]
	v_mfma_f32_16x16x32_bf16 v[34:37], v[182:185], v[198:201], v[34:37]
	v_mfma_f32_16x16x32_bf16 v[22:25], v[174:177], v[206:209], v[22:25]
	v_mfma_f32_16x16x32_bf16 v[18:21], v[182:185], v[206:209], v[18:21]
	v_mfma_f32_16x16x32_bf16 v[6:9], v[174:177], v[214:217], v[6:9]
	v_mfma_f32_16x16x32_bf16 v[2:5], v[182:185], v[214:217], v[2:5]
	s_setprio 0
	s_barrier
	s_add_i32 s70, 0, 0x18000
	v_add_u32_e32 v153, s70, v149
	s_add_i32 s71, 0, 0x1c000
	ds_read_b128 v[154:157], v153
	ds_read_b128 v[158:161], v153 offset:1024
	ds_read_b128 v[162:165], v153 offset:2048
	ds_read_b128 v[166:169], v153 offset:3072
	v_add_u32_e32 v153, s71, v149
	ds_read_b128 v[170:173], v153
	ds_read_b128 v[174:177], v153 offset:1024
	ds_read_b128 v[178:181], v153 offset:2048
	ds_read_b128 v[182:185], v153 offset:3072
	s_add_u32 s40, s40, 0x40000
	s_addc_u32 s41, s41, 0
	s_mov_b32 m0, s46
	v_lshl_add_u64 v[226:227], s[40:41], 0, v[136:137]
	ds_read_b128 v[186:189], v152 offset:32768
	ds_read_b128 v[190:193], v152 offset:33792
	ds_read_b128 v[194:197], v152 offset:34816
	ds_read_b128 v[198:201], v152 offset:35840
	ds_read_b128 v[202:205], v152 offset:36864
	ds_read_b128 v[206:209], v152 offset:37888
	ds_read_b128 v[210:213], v152 offset:38912
	ds_read_b128 v[214:217], v152 offset:39936
	global_load_lds_dwordx4 v[226:227], off
	v_lshl_add_u64 v[226:227], s[40:41], 0, v[132:133]
	s_mov_b32 m0, s47
	s_nop 0
	global_load_lds_dwordx4 v[226:227], off
	s_waitcnt vmcnt(8)
	s_waitcnt lgkmcnt(0)
	s_barrier
	s_setprio 1
	s_waitcnt lgkmcnt(0)
	v_mfma_f32_16x16x32_bf16 v[126:129], v[154:157], v[186:189], v[126:129]
	v_mfma_f32_16x16x32_bf16 v[122:125], v[162:165], v[186:189], v[122:125]
	v_mfma_f32_16x16x32_bf16 v[110:113], v[154:157], v[194:197], v[110:113]
	v_mfma_f32_16x16x32_bf16 v[106:109], v[162:165], v[194:197], v[106:109]
	v_mfma_f32_16x16x32_bf16 v[94:97], v[154:157], v[202:205], v[94:97]
	v_mfma_f32_16x16x32_bf16 v[90:93], v[162:165], v[202:205], v[90:93]
	v_mfma_f32_16x16x32_bf16 v[78:81], v[154:157], v[210:213], v[78:81]
	v_mfma_f32_16x16x32_bf16 v[74:77], v[162:165], v[210:213], v[74:77]
	v_mfma_f32_16x16x32_bf16 v[126:129], v[158:161], v[190:193], v[126:129]
	v_mfma_f32_16x16x32_bf16 v[122:125], v[166:169], v[190:193], v[122:125]
	v_mfma_f32_16x16x32_bf16 v[110:113], v[158:161], v[198:201], v[110:113]
	v_mfma_f32_16x16x32_bf16 v[106:109], v[166:169], v[198:201], v[106:109]
	v_mfma_f32_16x16x32_bf16 v[94:97], v[158:161], v[206:209], v[94:97]
	v_mfma_f32_16x16x32_bf16 v[90:93], v[166:169], v[206:209], v[90:93]
	v_mfma_f32_16x16x32_bf16 v[78:81], v[158:161], v[214:217], v[78:81]
	v_mfma_f32_16x16x32_bf16 v[74:77], v[166:169], v[214:217], v[74:77]
	s_setprio 0
	s_setprio 1
	v_mfma_f32_16x16x32_bf16 v[118:121], v[170:173], v[186:189], v[118:121]
	v_mfma_f32_16x16x32_bf16 v[114:117], v[178:181], v[186:189], v[114:117]
	v_mfma_f32_16x16x32_bf16 v[102:105], v[170:173], v[194:197], v[102:105]
	v_mfma_f32_16x16x32_bf16 v[98:101], v[178:181], v[194:197], v[98:101]
	v_mfma_f32_16x16x32_bf16 v[86:89], v[170:173], v[202:205], v[86:89]
	v_mfma_f32_16x16x32_bf16 v[82:85], v[178:181], v[202:205], v[82:85]
	v_mfma_f32_16x16x32_bf16 v[70:73], v[170:173], v[210:213], v[70:73]
	v_mfma_f32_16x16x32_bf16 v[66:69], v[178:181], v[210:213], v[66:69]
	v_mfma_f32_16x16x32_bf16 v[118:121], v[174:177], v[190:193], v[118:121]
	v_mfma_f32_16x16x32_bf16 v[114:117], v[182:185], v[190:193], v[114:117]
	v_mfma_f32_16x16x32_bf16 v[102:105], v[174:177], v[198:201], v[102:105]
	v_mfma_f32_16x16x32_bf16 v[98:101], v[182:185], v[198:201], v[98:101]
	v_mfma_f32_16x16x32_bf16 v[86:89], v[174:177], v[206:209], v[86:89]
	v_mfma_f32_16x16x32_bf16 v[82:85], v[182:185], v[206:209], v[82:85]
	v_mfma_f32_16x16x32_bf16 v[70:73], v[174:177], v[214:217], v[70:73]
	v_mfma_f32_16x16x32_bf16 v[66:69], v[182:185], v[214:217], v[66:69]
	s_setprio 0
	s_barrier
; #define PG8_STAGE(bufoff, gbase, voff) do { _Pragma("unroll") for (int _i = 0; _i < 2; ++_i) \
;         __builtin_amdgcn_global_load_lds((const unsigned*)((const char*)(gbase) + (voff)[_i]), (PG8_LAS unsigned*)(lds + (bufoff) + ldsw + _i * 8192), 16, 0, 0); } while (0)
; #define PG8_LDA(dst, b, h) do { _Pragma("unroll") for (int m = 0; m < 4; ++m) _Pragma("unroll") for (int k = 0; k < 2; ++k) dst[m][k] = *(const PG8_LAS bf16x8*)(lds + PG8_SA(b, h) + aoff + m * 2048 + k * 1024); } while (0)
; #define PG8_MMA(ai, bj, At, Bt) do { __builtin_amdgcn_s_setprio(1); _Pragma("unroll") for (int m = 0; m < 4; ++m) _Pragma("unroll") for (int n = 0; n < 2; ++n) _Pragma("unroll") for (int k = 0; k < 2; ++k) \
;         acc[ai][bj][m][n] = __builtin_amdgcn_mfma_f32_16x16x32_bf16(Bt[n][k], At[m][k], acc[ai][bj][m][n], 0, 0, 0); __builtin_amdgcn_s_setprio(0); } while (0)
; #define PG8_WAIT_V(n) asm volatile("s_waitcnt vmcnt(" #n ")" ::: "memory")
; #define PG8_WAIT_L(n) asm volatile("s_waitcnt lgkmcnt(" #n ")" ::: "memory")
; #define PG8_BAR __builtin_amdgcn_s_barrier()
; #define PG8_SCHED __builtin_amdgcn_sched_barrier(0)
; template <class Epi, class Sched, bool ALIGN_EPI = false, bool SP2 = false>
; __device__ __forceinline__ void gemm_phase(PG8_LAS unsigned char* lds, const Gemm g, const Sched& S, const Epi& E) {
;     ...
;         for (int t = 0; t < nt; t += 2) {
;     ...
;             PG8_LDA(At, 1, 1); PG8_STAGE(PG8_SB(1, 0), b3, voffB); PG8_STAGE(PG8_SB(1, 1), b3 + hstep, voffB); PG8_STAGE(PG8_SA(1, 0), a3, voffA);
;             PG8_WAIT_V(8); PG8_WAIT_L(0); PG8_BAR; PG8_MMA(1, 0, At, B0); PG8_MMA(1, 1, At, B1); PG8_BAR; PG8_SCHED;
	s_add_i32 s40, s70, s42
	v_lshl_add_u64 v[218:219], v[218:219], 0, s[8:9]
	s_mov_b32 m0, s40
	ds_read_b128 v[186:189], v152 offset:49152
	ds_read_b128 v[190:193], v152 offset:50176
	ds_read_b128 v[194:197], v152 offset:51200
	ds_read_b128 v[198:201], v152 offset:52224
	ds_read_b128 v[202:205], v152 offset:53248
	ds_read_b128 v[206:209], v152 offset:54272
	ds_read_b128 v[210:213], v152 offset:55296
	ds_read_b128 v[214:217], v152 offset:56320
	global_load_lds_dwordx4 v[218:219], off
	s_add_i32 m0, s40, 0x2000
	s_add_u32 s38, s38, 0x40080
	v_lshl_add_u64 v[218:219], v[220:221], 0, s[8:9]
	s_addc_u32 s39, s39, 0
	s_add_i32 s40, s71, s42
	global_load_lds_dwordx4 v[218:219], off
	v_lshl_add_u64 v[218:219], s[38:39], 0, v[134:135]
	s_mov_b32 m0, s40
	s_nop 0
	global_load_lds_dwordx4 v[218:219], off
	v_lshl_add_u64 v[218:219], s[38:39], 0, v[130:131]
	s_add_i32 m0, s40, 0x2000
	s_nop 0
	global_load_lds_dwordx4 v[218:219], off
	v_lshl_add_u64 v[218:219], v[222:223], 0, s[8:9]
	s_mov_b32 m0, s52
	s_nop 0
	global_load_lds_dwordx4 v[218:219], off
	v_lshl_add_u64 v[218:219], v[224:225], 0, s[8:9]
	s_mov_b32 m0, s53
	s_nop 0
	global_load_lds_dwordx4 v[218:219], off
	s_waitcnt vmcnt(8)
	s_waitcnt lgkmcnt(0)
	s_barrier
	s_setprio 1
	s_waitcnt lgkmcnt(0)
	v_mfma_f32_16x16x32_bf16 v[62:65], v[154:157], v[186:189], v[62:65]
	v_mfma_f32_16x16x32_bf16 v[58:61], v[162:165], v[186:189], v[58:61]
	v_mfma_f32_16x16x32_bf16 v[46:49], v[154:157], v[194:197], v[46:49]
	v_mfma_f32_16x16x32_bf16 v[42:45], v[162:165], v[194:197], v[42:45]
	v_mfma_f32_16x16x32_bf16 v[30:33], v[154:157], v[202:205], v[30:33]
	v_mfma_f32_16x16x32_bf16 v[26:29], v[162:165], v[202:205], v[26:29]
	v_mfma_f32_16x16x32_bf16 v[14:17], v[154:157], v[210:213], v[14:17]
	v_mfma_f32_16x16x32_bf16 v[10:13], v[162:165], v[210:213], v[10:13]
	v_mfma_f32_16x16x32_bf16 v[62:65], v[158:161], v[190:193], v[62:65]
	v_mfma_f32_16x16x32_bf16 v[58:61], v[166:169], v[190:193], v[58:61]
	v_mfma_f32_16x16x32_bf16 v[46:49], v[158:161], v[198:201], v[46:49]
	v_mfma_f32_16x16x32_bf16 v[42:45], v[166:169], v[198:201], v[42:45]
	v_mfma_f32_16x16x32_bf16 v[30:33], v[158:161], v[206:209], v[30:33]
	v_mfma_f32_16x16x32_bf16 v[26:29], v[166:169], v[206:209], v[26:29]
	v_mfma_f32_16x16x32_bf16 v[14:17], v[158:161], v[214:217], v[14:17]
	v_mfma_f32_16x16x32_bf16 v[10:13], v[166:169], v[214:217], v[10:13]
	s_setprio 0
	s_setprio 1
	v_mfma_f32_16x16x32_bf16 v[54:57], v[170:173], v[186:189], v[54:57]
	v_mfma_f32_16x16x32_bf16 v[50:53], v[178:181], v[186:189], v[50:53]
	v_mfma_f32_16x16x32_bf16 v[38:41], v[170:173], v[194:197], v[38:41]
	v_mfma_f32_16x16x32_bf16 v[34:37], v[178:181], v[194:197], v[34:37]
	v_mfma_f32_16x16x32_bf16 v[22:25], v[170:173], v[202:205], v[22:25]
	v_mfma_f32_16x16x32_bf16 v[18:21], v[178:181], v[202:205], v[18:21]
	v_mfma_f32_16x16x32_bf16 v[6:9], v[170:173], v[210:213], v[6:9]
	v_mfma_f32_16x16x32_bf16 v[2:5], v[178:181], v[210:213], v[2:5]
	v_mfma_f32_16x16x32_bf16 v[54:57], v[174:177], v[190:193], v[54:57]
	v_mfma_f32_16x16x32_bf16 v[50:53], v[182:185], v[190:193], v[50:53]
	v_mfma_f32_16x16x32_bf16 v[38:41], v[174:177], v[198:201], v[38:41]
	v_mfma_f32_16x16x32_bf16 v[34:37], v[182:185], v[198:201], v[34:37]
	v_mfma_f32_16x16x32_bf16 v[22:25], v[174:177], v[206:209], v[22:25]
	v_mfma_f32_16x16x32_bf16 v[18:21], v[182:185], v[206:209], v[18:21]
	v_mfma_f32_16x16x32_bf16 v[6:9], v[174:177], v[214:217], v[6:9]
	v_mfma_f32_16x16x32_bf16 v[2:5], v[182:185], v[214:217], v[2:5]
	s_setprio 0
	s_add_i32 s67, s67, 2
	s_add_u32 s36, s36, 0x100
	s_addc_u32 s37, s37, 0
	s_add_u32 s65, s65, 0x100
	s_addc_u32 s66, s66, 0
	s_cmp_gt_u32 s67, 13
	s_barrier
	s_cbranch_scc0 .LBB0_292
	s_and_b64 vcc, exec, s[12:13]
	s_cbranch_vccz .LBB0_295
	s_barrier

; #define PG8_STAGE(bufoff, gbase, voff) do { _Pragma("unroll") for (int _i = 0; _i < 2; ++_i) \
;         __builtin_amdgcn_global_load_lds((const unsigned*)((const char*)(gbase) + (voff)[_i]), (PG8_LAS unsigned*)(lds + (bufoff) + ldsw + _i * 8192), 16, 0, 0); } while (0)
; #define PG8_LDA(dst, b, h) do { _Pragma("unroll") for (int m = 0; m < 4; ++m) _Pragma("unroll") for (int k = 0; k < 2; ++k) dst[m][k] = *(const PG8_LAS bf16x8*)(lds + PG8_SA(b, h) + aoff + m * 2048 + k * 1024); } while (0)
; #define PG8_LDB(dst, b, h) do { _Pragma("unroll") for (int n = 0; n < 2; ++n) _Pragma("unroll") for (int k = 0; k < 2; ++k) dst[n][k] = *(const PG8_LAS bf16x8*)(lds + PG8_SB(b, h) + boff + n * 2048 + k * 1024); } while (0)
; #define PG8_MMA(ai, bj, At, Bt) do { __builtin_amdgcn_s_setprio(1); _Pragma("unroll") for (int m = 0; m < 4; ++m) _Pragma("unroll") for (int n = 0; n < 2; ++n) _Pragma("unroll") for (int k = 0; k < 2; ++k) \
;         acc[ai][bj][m][n] = __builtin_amdgcn_mfma_f32_16x16x32_bf16(Bt[n][k], At[m][k], acc[ai][bj][m][n], 0, 0, 0); __builtin_amdgcn_s_setprio(0); } while (0)
; #define PG8_WAIT_V(n) asm volatile("s_waitcnt vmcnt(" #n ")" ::: "memory")
; #define PG8_WAIT_L(n) asm volatile("s_waitcnt lgkmcnt(" #n ")" ::: "memory")
; #define PG8_BAR __builtin_amdgcn_s_barrier()
; #define PG8_SCHED __builtin_amdgcn_sched_barrier(0)
; template <class Epi, class Sched, bool ALIGN_EPI = false, bool SP2 = false>
; __device__ __forceinline__ void gemm_phase(PG8_LAS unsigned char* lds, const Gemm g, const Sched& S, const Epi& E) {
;     ...
;         for (int t = 0; t < nt; t += 2) {
;             const bool last = (t == nt - 2);
;             const char* a1 = cA + (size_t)(t + 1) * kstep;
;             const char* a2 = last ? nA : cA + (size_t)(t + 2) * kstep; const char* b2 = last ? nB : cB + (size_t)(t + 2) * kstep;
;             const char* a3 = a2 + kstep; const char* b3 = b2 + kstep;
;             if (last && has_next) S.a_ready(nxt);
;             if constexpr (SP2) {
;             PG8_LDB(B0, 0, 0); PG8_LDB(B1, 0, 1); PG8_SCHED; PG8_LDA(At, 0, 0); PG8_STAGE(PG8_SA(1, 1), a1 + hstep, voffA);
;             PG8_WAIT_V(8); PG8_WAIT_L(0); PG8_BAR; PG8_MMA(0, 0, At, B0); PG8_MMA(0, 1, At, B1); PG8_BAR; PG8_SCHED;
;             PG8_LDA(At, 0, 1); PG8_STAGE(PG8_SB(0, 0), b2, voffB); PG8_STAGE(PG8_SB(0, 1), b2 + hstep, voffB); PG8_STAGE(PG8_SA(0, 0), a2, voffA);
.LBB0_379:
	ds_read_b128 v[148:151], v228
	ds_read_b128 v[152:155], v228 offset:1024
	ds_read_b128 v[156:159], v228 offset:2048
	ds_read_b128 v[160:163], v228 offset:3072
	ds_read_b128 v[164:167], v229
	ds_read_b128 v[168:171], v229 offset:1024
	ds_read_b128 v[172:175], v229 offset:2048
	ds_read_b128 v[176:179], v229 offset:3072
	s_add_u32 s40, s38, 0xfff50080
	s_addc_u32 s41, s39, -1
	s_cmp_eq_u32 s52, 40
	s_cselect_b32 s43, s7, s41
	s_cselect_b32 s42, s6, s40
	s_cselect_b32 s41, s37, s49
	s_cselect_b32 s40, s36, s48
	v_lshl_add_u64 v[212:213], s[38:39], 0, v[138:139]
	s_add_i32 m0, s46, 0xc000
	ds_read_b128 v[180:183], v230
	ds_read_b128 v[184:187], v230 offset:1024
	ds_read_b128 v[188:191], v230 offset:2048
	ds_read_b128 v[192:195], v230 offset:3072
	ds_read_b128 v[196:199], v230 offset:4096
	ds_read_b128 v[200:203], v230 offset:5120
	ds_read_b128 v[204:207], v230 offset:6144
	ds_read_b128 v[208:211], v230 offset:7168
	global_load_lds_dwordx4 v[212:213], off
	v_lshl_add_u64 v[212:213], s[38:39], 0, v[140:141]
	s_add_i32 m0, s46, 0xe000
	s_nop 0
	global_load_lds_dwordx4 v[212:213], off
	s_waitcnt vmcnt(8)
	s_waitcnt lgkmcnt(0)
	s_barrier
	s_setprio 1
	s_waitcnt lgkmcnt(0)
	v_mfma_f32_16x16x32_bf16 v[126:129], v[148:151], v[180:183], v[126:129]
	v_mfma_f32_16x16x32_bf16 v[122:125], v[156:159], v[180:183], v[122:125]
	v_mfma_f32_16x16x32_bf16 v[82:85], v[148:151], v[188:191], v[82:85]
	v_mfma_f32_16x16x32_bf16 v[74:77], v[156:159], v[188:191], v[74:77]
	v_mfma_f32_16x16x32_bf16 v[94:97], v[148:151], v[196:199], v[94:97]
	v_mfma_f32_16x16x32_bf16 v[90:93], v[156:159], v[196:199], v[90:93]
	v_mfma_f32_16x16x32_bf16 v[110:113], v[148:151], v[204:207], v[110:113]
	v_mfma_f32_16x16x32_bf16 v[106:109], v[156:159], v[204:207], v[106:109]
	v_mfma_f32_16x16x32_bf16 v[126:129], v[152:155], v[184:187], v[126:129]
	v_mfma_f32_16x16x32_bf16 v[122:125], v[160:163], v[184:187], v[122:125]
	v_mfma_f32_16x16x32_bf16 v[82:85], v[152:155], v[192:195], v[82:85]
	v_mfma_f32_16x16x32_bf16 v[74:77], v[160:163], v[192:195], v[74:77]
	v_mfma_f32_16x16x32_bf16 v[94:97], v[152:155], v[200:203], v[94:97]
	v_mfma_f32_16x16x32_bf16 v[90:93], v[160:163], v[200:203], v[90:93]
	v_mfma_f32_16x16x32_bf16 v[110:113], v[152:155], v[208:211], v[110:113]
	v_mfma_f32_16x16x32_bf16 v[106:109], v[160:163], v[208:211], v[106:109]
	s_setprio 0
	s_setprio 1
	v_mfma_f32_16x16x32_bf16 v[62:65], v[164:167], v[180:183], v[62:65]
	v_mfma_f32_16x16x32_bf16 v[58:61], v[172:175], v[180:183], v[58:61]
	v_mfma_f32_16x16x32_bf16 v[54:57], v[164:167], v[188:191], v[54:57]
	v_mfma_f32_16x16x32_bf16 v[50:53], v[172:175], v[188:191], v[50:53]
	v_mfma_f32_16x16x32_bf16 v[46:49], v[164:167], v[196:199], v[46:49]
	v_mfma_f32_16x16x32_bf16 v[42:45], v[172:175], v[196:199], v[42:45]
	v_mfma_f32_16x16x32_bf16 v[38:41], v[164:167], v[204:207], v[38:41]
	v_mfma_f32_16x16x32_bf16 v[34:37], v[172:175], v[204:207], v[34:37]
	v_mfma_f32_16x16x32_bf16 v[62:65], v[168:171], v[184:187], v[62:65]
	v_mfma_f32_16x16x32_bf16 v[58:61], v[176:179], v[184:187], v[58:61]
	v_mfma_f32_16x16x32_bf16 v[54:57], v[168:171], v[192:195], v[54:57]
	v_mfma_f32_16x16x32_bf16 v[50:53], v[176:179], v[192:195], v[50:53]
	v_mfma_f32_16x16x32_bf16 v[46:49], v[168:171], v[200:203], v[46:49]
	v_mfma_f32_16x16x32_bf16 v[42:45], v[176:179], v[200:203], v[42:45]
	v_mfma_f32_16x16x32_bf16 v[38:41], v[168:171], v[208:211], v[38:41]
	v_mfma_f32_16x16x32_bf16 v[34:37], v[176:179], v[208:211], v[34:37]
	s_setprio 0
	s_barrier
	s_add_i32 s53, s78, s45
	v_lshl_add_u64 v[212:213], s[40:41], 0, v[132:133]
	s_mov_b32 m0, s53
	ds_read_b128 v[180:183], v230 offset:16384
	ds_read_b128 v[184:187], v230 offset:17408
	ds_read_b128 v[188:191], v230 offset:18432
	ds_read_b128 v[192:195], v230 offset:19456
	ds_read_b128 v[196:199], v230 offset:20480
	ds_read_b128 v[200:203], v230 offset:21504
	ds_read_b128 v[204:207], v230 offset:22528
	ds_read_b128 v[208:211], v230 offset:23552
	global_load_lds_dwordx4 v[212:213], off
	s_add_i32 m0, s53, 0x2000
	s_add_u32 s54, s40, 0xb0000
	v_lshl_add_u64 v[214:215], s[40:41], 0, v[136:137]
	s_addc_u32 s55, s41, 0
	s_add_i32 s53, s79, s45
	global_load_lds_dwordx4 v[214:215], off
	v_lshl_add_u64 v[216:217], s[54:55], 0, v[132:133]
	s_mov_b32 m0, s53
	v_lshl_add_u64 v[218:219], s[42:43], 0, v[134:135]
	global_load_lds_dwordx4 v[216:217], off
	v_lshl_add_u64 v[216:217], s[54:55], 0, v[136:137]
	s_add_i32 m0, s53, 0x2000
	s_nop 0
	global_load_lds_dwordx4 v[216:217], off
	v_lshl_add_u64 v[216:217], s[42:43], 0, v[130:131]
	s_mov_b32 m0, s46
	s_nop 0
	global_load_lds_dwordx4 v[216:217], off
	s_mov_b32 m0, s47
	s_nop 0
	global_load_lds_dwordx4 v[218:219], off
	s_waitcnt vmcnt(8)
	s_waitcnt lgkmcnt(0)
	s_barrier
; #define PG8_STAGE(bufoff, gbase, voff) do { _Pragma("unroll") for (int _i = 0; _i < 2; ++_i) \
;         __builtin_amdgcn_global_load_lds((const unsigned*)((const char*)(gbase) + (voff)[_i]), (PG8_LAS unsigned*)(lds + (bufoff) + ldsw + _i * 8192), 16, 0, 0); } while (0)
; #define PG8_LDA(dst, b, h) do { _Pragma("unroll") for (int m = 0; m < 4; ++m) _Pragma("unroll") for (int k = 0; k < 2; ++k) dst[m][k] = *(const PG8_LAS bf16x8*)(lds + PG8_SA(b, h) + aoff + m * 2048 + k * 1024); } while (0)
; #define PG8_LDB(dst, b, h) do { _Pragma("unroll") for (int n = 0; n < 2; ++n) _Pragma("unroll") for (int k = 0; k < 2; ++k) dst[n][k] = *(const PG8_LAS bf16x8*)(lds + PG8_SB(b, h) + boff + n * 2048 + k * 1024); } while (0)
; #define PG8_MMA(ai, bj, At, Bt) do { __builtin_amdgcn_s_setprio(1); _Pragma("unroll") for (int m = 0; m < 4; ++m) _Pragma("unroll") for (int n = 0; n < 2; ++n) _Pragma("unroll") for (int k = 0; k < 2; ++k) \
;         acc[ai][bj][m][n] = __builtin_amdgcn_mfma_f32_16x16x32_bf16(Bt[n][k], At[m][k], acc[ai][bj][m][n], 0, 0, 0); __builtin_amdgcn_s_setprio(0); } while (0)
; #define PG8_WAIT_V(n) asm volatile("s_waitcnt vmcnt(" #n ")" ::: "memory")
; #define PG8_WAIT_L(n) asm volatile("s_waitcnt lgkmcnt(" #n ")" ::: "memory")
; #define PG8_BAR __builtin_amdgcn_s_barrier()
; #define PG8_SCHED __builtin_amdgcn_sched_barrier(0)
; template <class Epi, class Sched, bool ALIGN_EPI = false, bool SP2 = false>
; __device__ __forceinline__ void gemm_phase(PG8_LAS unsigned char* lds, const Gemm g, const Sched& S, const Epi& E) {
;     ...
;             PG8_WAIT_V(8); PG8_WAIT_L(0); PG8_BAR; PG8_MMA(1, 0, At, B0); PG8_MMA(1, 1, At, B1); PG8_BAR; PG8_SCHED;
;             PG8_LDB(B0, 1, 0); PG8_LDB(B1, 1, 1); PG8_SCHED; PG8_LDA(At, 1, 0); PG8_STAGE(PG8_SA(0, 1), a2 + hstep, voffA);
;             PG8_WAIT_V(8); PG8_WAIT_L(0); PG8_BAR; PG8_MMA(0, 0, At, B0); PG8_MMA(0, 1, At, B1); PG8_BAR; PG8_SCHED;
;             PG8_LDA(At, 1, 1); PG8_STAGE(PG8_SB(1, 0), b3, voffB); PG8_STAGE(PG8_SB(1, 1), b3 + hstep, voffB); PG8_STAGE(PG8_SA(1, 0), a3, voffA);
	s_setprio 1
	s_waitcnt lgkmcnt(0)
	v_mfma_f32_16x16x32_bf16 v[118:121], v[148:151], v[180:183], v[118:121]
	v_mfma_f32_16x16x32_bf16 v[114:117], v[156:159], v[180:183], v[114:117]
	v_mfma_f32_16x16x32_bf16 v[102:105], v[148:151], v[188:191], v[102:105]
	v_mfma_f32_16x16x32_bf16 v[98:101], v[156:159], v[188:191], v[98:101]
	v_mfma_f32_16x16x32_bf16 v[86:89], v[148:151], v[196:199], v[86:89]
	v_mfma_f32_16x16x32_bf16 v[78:81], v[156:159], v[196:199], v[78:81]
	v_mfma_f32_16x16x32_bf16 v[70:73], v[148:151], v[204:207], v[70:73]
	v_mfma_f32_16x16x32_bf16 v[66:69], v[156:159], v[204:207], v[66:69]
	v_mfma_f32_16x16x32_bf16 v[118:121], v[152:155], v[184:187], v[118:121]
	v_mfma_f32_16x16x32_bf16 v[114:117], v[160:163], v[184:187], v[114:117]
	v_mfma_f32_16x16x32_bf16 v[102:105], v[152:155], v[192:195], v[102:105]
	v_mfma_f32_16x16x32_bf16 v[98:101], v[160:163], v[192:195], v[98:101]
	v_mfma_f32_16x16x32_bf16 v[86:89], v[152:155], v[200:203], v[86:89]
	v_mfma_f32_16x16x32_bf16 v[78:81], v[160:163], v[200:203], v[78:81]
	v_mfma_f32_16x16x32_bf16 v[70:73], v[152:155], v[208:211], v[70:73]
	v_mfma_f32_16x16x32_bf16 v[66:69], v[160:163], v[208:211], v[66:69]
	s_setprio 0
	s_setprio 1
	v_mfma_f32_16x16x32_bf16 v[30:33], v[164:167], v[180:183], v[30:33]
	v_mfma_f32_16x16x32_bf16 v[26:29], v[172:175], v[180:183], v[26:29]
	v_mfma_f32_16x16x32_bf16 v[22:25], v[164:167], v[188:191], v[22:25]
	v_mfma_f32_16x16x32_bf16 v[18:21], v[172:175], v[188:191], v[18:21]
	v_mfma_f32_16x16x32_bf16 v[14:17], v[164:167], v[196:199], v[14:17]
	v_mfma_f32_16x16x32_bf16 v[10:13], v[172:175], v[196:199], v[10:13]
	v_mfma_f32_16x16x32_bf16 v[6:9], v[164:167], v[204:207], v[6:9]
	v_mfma_f32_16x16x32_bf16 v[2:5], v[172:175], v[204:207], v[2:5]
	v_mfma_f32_16x16x32_bf16 v[30:33], v[168:171], v[184:187], v[30:33]
	v_mfma_f32_16x16x32_bf16 v[26:29], v[176:179], v[184:187], v[26:29]
	v_mfma_f32_16x16x32_bf16 v[22:25], v[168:171], v[192:195], v[22:25]
	v_mfma_f32_16x16x32_bf16 v[18:21], v[176:179], v[192:195], v[18:21]
	v_mfma_f32_16x16x32_bf16 v[14:17], v[168:171], v[200:203], v[14:17]
	v_mfma_f32_16x16x32_bf16 v[10:13], v[176:179], v[200:203], v[10:13]
	v_mfma_f32_16x16x32_bf16 v[6:9], v[168:171], v[208:211], v[6:9]
	v_mfma_f32_16x16x32_bf16 v[2:5], v[176:179], v[208:211], v[2:5]
	s_setprio 0
	s_barrier
	s_add_i32 s53, 0, 0x18000
	s_add_i32 s54, 0, 0x1c000
	v_add_u32_e32 v160, s53, v227
	v_add_u32_e32 v176, s54, v227
	ds_read_b128 v[148:151], v160
	ds_read_b128 v[152:155], v160 offset:1024
	ds_read_b128 v[156:159], v160 offset:2048
	ds_read_b128 v[160:163], v160 offset:3072
	ds_read_b128 v[164:167], v176
	ds_read_b128 v[168:171], v176 offset:1024
	ds_read_b128 v[172:175], v176 offset:2048
	ds_read_b128 v[176:179], v176 offset:3072
	s_add_u32 s42, s42, 0xb0000
	s_addc_u32 s43, s43, 0
	s_mov_b32 m0, s51
	v_lshl_add_u64 v[220:221], s[42:43], 0, v[130:131]
	ds_read_b128 v[180:183], v230 offset:32768
	ds_read_b128 v[184:187], v230 offset:33792
	ds_read_b128 v[188:191], v230 offset:34816
	ds_read_b128 v[192:195], v230 offset:35840
	ds_read_b128 v[196:199], v230 offset:36864
	ds_read_b128 v[200:203], v230 offset:37888
	ds_read_b128 v[204:207], v230 offset:38912
	ds_read_b128 v[208:211], v230 offset:39936
	global_load_lds_dwordx4 v[220:221], off
	v_lshl_add_u64 v[220:221], s[42:43], 0, v[134:135]
	s_mov_b32 m0, s64
	s_nop 0
	global_load_lds_dwordx4 v[220:221], off
	s_waitcnt vmcnt(8)
	s_waitcnt lgkmcnt(0)
	s_barrier
	s_setprio 1
	s_waitcnt lgkmcnt(0)
	v_mfma_f32_16x16x32_bf16 v[126:129], v[148:151], v[180:183], v[126:129]
	v_mfma_f32_16x16x32_bf16 v[122:125], v[156:159], v[180:183], v[122:125]
	v_mfma_f32_16x16x32_bf16 v[82:85], v[148:151], v[188:191], v[82:85]
	v_mfma_f32_16x16x32_bf16 v[74:77], v[156:159], v[188:191], v[74:77]
	v_mfma_f32_16x16x32_bf16 v[94:97], v[148:151], v[196:199], v[94:97]
	v_mfma_f32_16x16x32_bf16 v[90:93], v[156:159], v[196:199], v[90:93]
	v_mfma_f32_16x16x32_bf16 v[110:113], v[148:151], v[204:207], v[110:113]
	v_mfma_f32_16x16x32_bf16 v[106:109], v[156:159], v[204:207], v[106:109]
	v_mfma_f32_16x16x32_bf16 v[126:129], v[152:155], v[184:187], v[126:129]
	v_mfma_f32_16x16x32_bf16 v[122:125], v[160:163], v[184:187], v[122:125]
	v_mfma_f32_16x16x32_bf16 v[82:85], v[152:155], v[192:195], v[82:85]
	v_mfma_f32_16x16x32_bf16 v[74:77], v[160:163], v[192:195], v[74:77]
	v_mfma_f32_16x16x32_bf16 v[94:97], v[152:155], v[200:203], v[94:97]
	v_mfma_f32_16x16x32_bf16 v[90:93], v[160:163], v[200:203], v[90:93]
	v_mfma_f32_16x16x32_bf16 v[110:113], v[152:155], v[208:211], v[110:113]
	v_mfma_f32_16x16x32_bf16 v[106:109], v[160:163], v[208:211], v[106:109]
	s_setprio 0
	s_setprio 1
	v_mfma_f32_16x16x32_bf16 v[62:65], v[164:167], v[180:183], v[62:65]
	v_mfma_f32_16x16x32_bf16 v[58:61], v[172:175], v[180:183], v[58:61]
	v_mfma_f32_16x16x32_bf16 v[54:57], v[164:167], v[188:191], v[54:57]
	v_mfma_f32_16x16x32_bf16 v[50:53], v[172:175], v[188:191], v[50:53]
	v_mfma_f32_16x16x32_bf16 v[46:49], v[164:167], v[196:199], v[46:49]
	v_mfma_f32_16x16x32_bf16 v[42:45], v[172:175], v[196:199], v[42:45]
	v_mfma_f32_16x16x32_bf16 v[38:41], v[164:167], v[204:207], v[38:41]
	v_mfma_f32_16x16x32_bf16 v[34:37], v[172:175], v[204:207], v[34:37]
	v_mfma_f32_16x16x32_bf16 v[62:65], v[168:171], v[184:187], v[62:65]
	v_mfma_f32_16x16x32_bf16 v[58:61], v[176:179], v[184:187], v[58:61]
	v_mfma_f32_16x16x32_bf16 v[54:57], v[168:171], v[192:195], v[54:57]
	v_mfma_f32_16x16x32_bf16 v[50:53], v[176:179], v[192:195], v[50:53]
	v_mfma_f32_16x16x32_bf16 v[46:49], v[168:171], v[200:203], v[46:49]
	v_mfma_f32_16x16x32_bf16 v[42:45], v[176:179], v[200:203], v[42:45]
	v_mfma_f32_16x16x32_bf16 v[38:41], v[168:171], v[208:211], v[38:41]
	v_mfma_f32_16x16x32_bf16 v[34:37], v[176:179], v[208:211], v[34:37]
	s_setprio 0
	s_barrier
; #define PG8_STAGE(bufoff, gbase, voff) do { _Pragma("unroll") for (int _i = 0; _i < 2; ++_i) \
;         __builtin_amdgcn_global_load_lds((const unsigned*)((const char*)(gbase) + (voff)[_i]), (PG8_LAS unsigned*)(lds + (bufoff) + ldsw + _i * 8192), 16, 0, 0); } while (0)
; #define PG8_LDA(dst, b, h) do { _Pragma("unroll") for (int m = 0; m < 4; ++m) _Pragma("unroll") for (int k = 0; k < 2; ++k) dst[m][k] = *(const PG8_LAS bf16x8*)(lds + PG8_SA(b, h) + aoff + m * 2048 + k * 1024); } while (0)
; #define PG8_MMA(ai, bj, At, Bt) do { __builtin_amdgcn_s_setprio(1); _Pragma("unroll") for (int m = 0; m < 4; ++m) _Pragma("unroll") for (int n = 0; n < 2; ++n) _Pragma("unroll") for (int k = 0; k < 2; ++k) \
;         acc[ai][bj][m][n] = __builtin_amdgcn_mfma_f32_16x16x32_bf16(Bt[n][k], At[m][k], acc[ai][bj][m][n], 0, 0, 0); __builtin_amdgcn_s_setprio(0); } while (0)
; #define PG8_WAIT_V(n) asm volatile("s_waitcnt vmcnt(" #n ")" ::: "memory")
; #define PG8_WAIT_L(n) asm volatile("s_waitcnt lgkmcnt(" #n ")" ::: "memory")
; #define PG8_BAR __builtin_amdgcn_s_barrier()
; #define PG8_SCHED __builtin_amdgcn_sched_barrier(0)
; template <class Epi, class Sched, bool ALIGN_EPI = false, bool SP2 = false>
; __device__ __forceinline__ void gemm_phase(PG8_LAS unsigned char* lds, const Gemm g, const Sched& S, const Epi& E) {
;     ...
;         for (int t = 0; t < nt; t += 2) {
;     ...
;             PG8_LDA(At, 1, 1); PG8_STAGE(PG8_SB(1, 0), b3, voffB); PG8_STAGE(PG8_SB(1, 1), b3 + hstep, voffB); PG8_STAGE(PG8_SA(1, 0), a3, voffA);
;             PG8_WAIT_V(8); PG8_WAIT_L(0); PG8_BAR; PG8_MMA(1, 0, At, B0); PG8_MMA(1, 1, At, B1); PG8_BAR; PG8_SCHED;
	s_add_i32 s42, s53, s45
	v_lshl_add_u64 v[212:213], v[212:213], 0, s[24:25]
	s_mov_b32 m0, s42
	ds_read_b128 v[180:183], v230 offset:49152
	ds_read_b128 v[184:187], v230 offset:50176
	ds_read_b128 v[188:191], v230 offset:51200
	ds_read_b128 v[192:195], v230 offset:52224
	ds_read_b128 v[196:199], v230 offset:53248
	ds_read_b128 v[200:203], v230 offset:54272
	ds_read_b128 v[204:207], v230 offset:55296
	ds_read_b128 v[208:211], v230 offset:56320
	global_load_lds_dwordx4 v[212:213], off
	s_add_i32 m0, s42, 0x2000
	s_add_u32 s40, s40, 0xb0080
	v_lshl_add_u64 v[212:213], v[214:215], 0, s[24:25]
	s_addc_u32 s41, s41, 0
	s_add_i32 s42, s54, s45
	global_load_lds_dwordx4 v[212:213], off
	v_lshl_add_u64 v[212:213], s[40:41], 0, v[132:133]
	s_mov_b32 m0, s42
	s_nop 0
	global_load_lds_dwordx4 v[212:213], off
	v_lshl_add_u64 v[212:213], s[40:41], 0, v[136:137]
	s_add_i32 m0, s42, 0x2000
	s_nop 0
	global_load_lds_dwordx4 v[212:213], off
	v_lshl_add_u64 v[212:213], v[216:217], 0, s[24:25]
	s_mov_b32 m0, s70
	s_nop 0
	global_load_lds_dwordx4 v[212:213], off
	v_lshl_add_u64 v[212:213], v[218:219], 0, s[24:25]
	s_mov_b32 m0, s71
	s_nop 0
	global_load_lds_dwordx4 v[212:213], off
	s_waitcnt vmcnt(8)
	s_waitcnt lgkmcnt(0)
	s_barrier
	s_setprio 1
	s_waitcnt lgkmcnt(0)
	v_mfma_f32_16x16x32_bf16 v[118:121], v[148:151], v[180:183], v[118:121]
	v_mfma_f32_16x16x32_bf16 v[114:117], v[156:159], v[180:183], v[114:117]
	v_mfma_f32_16x16x32_bf16 v[102:105], v[148:151], v[188:191], v[102:105]
	v_mfma_f32_16x16x32_bf16 v[98:101], v[156:159], v[188:191], v[98:101]
	v_mfma_f32_16x16x32_bf16 v[86:89], v[148:151], v[196:199], v[86:89]
	v_mfma_f32_16x16x32_bf16 v[78:81], v[156:159], v[196:199], v[78:81]
	v_mfma_f32_16x16x32_bf16 v[70:73], v[148:151], v[204:207], v[70:73]
	v_mfma_f32_16x16x32_bf16 v[66:69], v[156:159], v[204:207], v[66:69]
	v_mfma_f32_16x16x32_bf16 v[118:121], v[152:155], v[184:187], v[118:121]
	v_mfma_f32_16x16x32_bf16 v[114:117], v[160:163], v[184:187], v[114:117]
	v_mfma_f32_16x16x32_bf16 v[102:105], v[152:155], v[192:195], v[102:105]
	v_mfma_f32_16x16x32_bf16 v[98:101], v[160:163], v[192:195], v[98:101]
	v_mfma_f32_16x16x32_bf16 v[86:89], v[152:155], v[200:203], v[86:89]
	v_mfma_f32_16x16x32_bf16 v[78:81], v[160:163], v[200:203], v[78:81]
	v_mfma_f32_16x16x32_bf16 v[70:73], v[152:155], v[208:211], v[70:73]
	v_mfma_f32_16x16x32_bf16 v[66:69], v[160:163], v[208:211], v[66:69]
	s_setprio 0
	s_setprio 1
	v_mfma_f32_16x16x32_bf16 v[30:33], v[164:167], v[180:183], v[30:33]
	v_mfma_f32_16x16x32_bf16 v[26:29], v[172:175], v[180:183], v[26:29]
	v_mfma_f32_16x16x32_bf16 v[22:25], v[164:167], v[188:191], v[22:25]
	v_mfma_f32_16x16x32_bf16 v[18:21], v[172:175], v[188:191], v[18:21]
	v_mfma_f32_16x16x32_bf16 v[14:17], v[164:167], v[196:199], v[14:17]
	v_mfma_f32_16x16x32_bf16 v[10:13], v[172:175], v[196:199], v[10:13]
	v_mfma_f32_16x16x32_bf16 v[6:9], v[164:167], v[204:207], v[6:9]
	v_mfma_f32_16x16x32_bf16 v[2:5], v[172:175], v[204:207], v[2:5]
	v_mfma_f32_16x16x32_bf16 v[30:33], v[168:171], v[184:187], v[30:33]
	v_mfma_f32_16x16x32_bf16 v[26:29], v[176:179], v[184:187], v[26:29]
	v_mfma_f32_16x16x32_bf16 v[22:25], v[168:171], v[192:195], v[22:25]
	v_mfma_f32_16x16x32_bf16 v[18:21], v[176:179], v[192:195], v[18:21]
	v_mfma_f32_16x16x32_bf16 v[14:17], v[168:171], v[200:203], v[14:17]
	v_mfma_f32_16x16x32_bf16 v[10:13], v[176:179], v[200:203], v[10:13]
	v_mfma_f32_16x16x32_bf16 v[6:9], v[168:171], v[208:211], v[6:9]
	v_mfma_f32_16x16x32_bf16 v[2:5], v[176:179], v[208:211], v[2:5]
	s_setprio 0
	s_add_i32 s52, s52, 2
	s_add_u32 s38, s38, 0x100
	s_addc_u32 s39, s39, 0
	s_add_u32 s48, s48, 0x100
	s_addc_u32 s49, s49, 0
	s_cmp_gt_u32 s52, 41
	s_barrier
	s_cbranch_scc0 .LBB0_379
	s_and_b64 vcc, exec, s[26:27]
	s_cbranch_vccz .LBB0_382
	s_barrier

; #define PG8_STAGE(bufoff, gbase, voff) do { _Pragma("unroll") for (int _i = 0; _i < 2; ++_i) \
;         __builtin_amdgcn_global_load_lds((const unsigned*)((const char*)(gbase) + (voff)[_i]), (PG8_LAS unsigned*)(lds + (bufoff) + ldsw + _i * 8192), 16, 0, 0); } while (0)
; #define PG8_LDA(dst, b, h) do { _Pragma("unroll") for (int m = 0; m < 4; ++m) _Pragma("unroll") for (int k = 0; k < 2; ++k) dst[m][k] = *(const PG8_LAS bf16x8*)(lds + PG8_SA(b, h) + aoff + m * 2048 + k * 1024); } while (0)
; #define PG8_LDB(dst, b, h) do { _Pragma("unroll") for (int n = 0; n < 2; ++n) _Pragma("unroll") for (int k = 0; k < 2; ++k) dst[n][k] = *(const PG8_LAS bf16x8*)(lds + PG8_SB(b, h) + boff + n * 2048 + k * 1024); } while (0)
; #define PG8_MMA(ai, bj, At, Bt) do { __builtin_amdgcn_s_setprio(1); _Pragma("unroll") for (int m = 0; m < 4; ++m) _Pragma("unroll") for (int n = 0; n < 2; ++n) _Pragma("unroll") for (int k = 0; k < 2; ++k) \
;         acc[ai][bj][m][n] = __builtin_amdgcn_mfma_f32_16x16x32_bf16(Bt[n][k], At[m][k], acc[ai][bj][m][n], 0, 0, 0); __builtin_amdgcn_s_setprio(0); } while (0)
; #define PG8_WAIT_V(n) asm volatile("s_waitcnt vmcnt(" #n ")" ::: "memory")
; #define PG8_WAIT_L(n) asm volatile("s_waitcnt lgkmcnt(" #n ")" ::: "memory")
; #define PG8_BAR __builtin_amdgcn_s_barrier()
; #define PG8_SCHED __builtin_amdgcn_sched_barrier(0)
; template <class Epi, class Sched, bool ALIGN_EPI = false, bool SP2 = false>
; __device__ __forceinline__ void gemm_phase(PG8_LAS unsigned char* lds, const Gemm g, const Sched& S, const Epi& E) {
;     ...
;         for (int t = 0; t < nt; t += 2) {
;             const bool last = (t == nt - 2);
;             const char* a1 = cA + (size_t)(t + 1) * kstep;
;             const char* a2 = last ? nA : cA + (size_t)(t + 2) * kstep; const char* b2 = last ? nB : cB + (size_t)(t + 2) * kstep;
;             const char* a3 = a2 + kstep; const char* b3 = b2 + kstep;
;             if (last && has_next) S.a_ready(nxt);
;             if constexpr (SP2) {
;             PG8_LDB(B0, 0, 0); PG8_LDB(B1, 0, 1); PG8_SCHED; PG8_LDA(At, 0, 0); PG8_STAGE(PG8_SA(1, 1), a1 + hstep, voffA);
;             PG8_WAIT_V(8); PG8_WAIT_L(0); PG8_BAR; PG8_MMA(0, 0, At, B0); PG8_MMA(0, 1, At, B1); PG8_BAR; PG8_SCHED;
;             PG8_LDA(At, 0, 1); PG8_STAGE(PG8_SB(0, 0), b2, voffB); PG8_STAGE(PG8_SB(0, 1), b2 + hstep, voffB); PG8_STAGE(PG8_SA(0, 0), a2, voffA);
.LBB0_481:
	ds_read_b128 v[22:25], v201
	ds_read_b128 v[30:33], v201 offset:1024
	ds_read_b128 v[38:41], v201 offset:2048
	ds_read_b128 v[46:49], v201 offset:3072
	ds_read_b128 v[166:169], v202
	ds_read_b128 v[170:173], v202 offset:1024
	ds_read_b128 v[174:177], v202 offset:2048
	ds_read_b128 v[178:181], v202 offset:3072
	s_add_u32 s46, s8, 0xfffc0080
	s_addc_u32 s47, s9, -1
	s_cmp_eq_u32 s48, 12
	s_cselect_b32 s65, s7, s47
	s_cselect_b32 s64, s11, s46
	s_cselect_b32 s47, s12, s41
	s_cselect_b32 s46, s33, s39
	v_lshl_add_u64 v[198:199], s[8:9], 0, v[156:157]
	s_add_i32 m0, s66, 0xc000
	ds_read_b128 v[182:185], v203
	ds_read_b128 v[186:189], v203 offset:1024
	ds_read_b128 v[190:193], v203 offset:2048
	ds_read_b128 v[194:197], v203 offset:3072
	ds_read_b128 v[206:209], v203 offset:4096
	ds_read_b128 v[210:213], v203 offset:5120
	ds_read_b128 v[214:217], v203 offset:6144
	ds_read_b128 v[218:221], v203 offset:7168
	global_load_lds_dwordx4 v[198:199], off
	v_lshl_add_u64 v[198:199], s[8:9], 0, v[158:159]
	s_add_i32 m0, s66, 0xe000
	s_nop 0
	global_load_lds_dwordx4 v[198:199], off
	s_waitcnt vmcnt(8)
	s_waitcnt lgkmcnt(0)
	s_barrier
	s_setprio 1
	s_waitcnt lgkmcnt(0)
	v_mfma_f32_16x16x32_bf16 v[142:145], v[22:25], v[182:185], v[142:145]
	v_mfma_f32_16x16x32_bf16 v[138:141], v[38:41], v[182:185], v[138:141]
	v_mfma_f32_16x16x32_bf16 v[126:129], v[22:25], v[190:193], v[126:129]
	v_mfma_f32_16x16x32_bf16 v[122:125], v[38:41], v[190:193], v[122:125]
	v_mfma_f32_16x16x32_bf16 v[110:113], v[22:25], v[206:209], v[110:113]
	v_mfma_f32_16x16x32_bf16 v[106:109], v[38:41], v[206:209], v[106:109]
	v_mfma_f32_16x16x32_bf16 v[94:97], v[22:25], v[214:217], v[94:97]
	v_mfma_f32_16x16x32_bf16 v[90:93], v[38:41], v[214:217], v[90:93]
	v_mfma_f32_16x16x32_bf16 v[142:145], v[30:33], v[186:189], v[142:145]
	v_mfma_f32_16x16x32_bf16 v[138:141], v[46:49], v[186:189], v[138:141]
	v_mfma_f32_16x16x32_bf16 v[126:129], v[30:33], v[194:197], v[126:129]
	v_mfma_f32_16x16x32_bf16 v[122:125], v[46:49], v[194:197], v[122:125]
	v_mfma_f32_16x16x32_bf16 v[110:113], v[30:33], v[210:213], v[110:113]
	v_mfma_f32_16x16x32_bf16 v[106:109], v[46:49], v[210:213], v[106:109]
	v_mfma_f32_16x16x32_bf16 v[94:97], v[30:33], v[218:221], v[94:97]
	v_mfma_f32_16x16x32_bf16 v[90:93], v[46:49], v[218:221], v[90:93]
	s_setprio 0
	s_setprio 1
	v_mfma_f32_16x16x32_bf16 v[134:137], v[166:169], v[182:185], v[134:137]
	v_mfma_f32_16x16x32_bf16 v[130:133], v[174:177], v[182:185], v[130:133]
	v_mfma_f32_16x16x32_bf16 v[118:121], v[166:169], v[190:193], v[118:121]
	v_mfma_f32_16x16x32_bf16 v[114:117], v[174:177], v[190:193], v[114:117]
	v_mfma_f32_16x16x32_bf16 v[102:105], v[166:169], v[206:209], v[102:105]
	v_mfma_f32_16x16x32_bf16 v[98:101], v[174:177], v[206:209], v[98:101]
	v_mfma_f32_16x16x32_bf16 v[86:89], v[166:169], v[214:217], v[86:89]
	v_mfma_f32_16x16x32_bf16 v[82:85], v[174:177], v[214:217], v[82:85]
	v_mfma_f32_16x16x32_bf16 v[134:137], v[170:173], v[186:189], v[134:137]
	v_mfma_f32_16x16x32_bf16 v[130:133], v[178:181], v[186:189], v[130:133]
	v_mfma_f32_16x16x32_bf16 v[118:121], v[170:173], v[194:197], v[118:121]
	v_mfma_f32_16x16x32_bf16 v[114:117], v[178:181], v[194:197], v[114:117]
	v_mfma_f32_16x16x32_bf16 v[102:105], v[170:173], v[210:213], v[102:105]
	v_mfma_f32_16x16x32_bf16 v[98:101], v[178:181], v[210:213], v[98:101]
	v_mfma_f32_16x16x32_bf16 v[86:89], v[170:173], v[218:221], v[86:89]
	v_mfma_f32_16x16x32_bf16 v[82:85], v[178:181], v[218:221], v[82:85]
	s_setprio 0
	s_barrier
	s_add_i32 s49, s80, s51
	v_lshl_add_u64 v[198:199], s[46:47], 0, v[150:151]
	s_mov_b32 m0, s49
	ds_read_b128 v[182:185], v203 offset:16384
	ds_read_b128 v[186:189], v203 offset:17408
	ds_read_b128 v[190:193], v203 offset:18432
	ds_read_b128 v[194:197], v203 offset:19456
	ds_read_b128 v[206:209], v203 offset:20480
	ds_read_b128 v[210:213], v203 offset:21504
	ds_read_b128 v[214:217], v203 offset:22528
	ds_read_b128 v[218:221], v203 offset:23552
	global_load_lds_dwordx4 v[198:199], off
	s_add_i32 m0, s49, 0x2000
	s_add_u32 s52, s46, 0x40000
	v_lshl_add_u64 v[222:223], s[46:47], 0, v[154:155]
	s_addc_u32 s53, s47, 0
	s_add_i32 s49, s81, s51
	global_load_lds_dwordx4 v[222:223], off
	v_lshl_add_u64 v[224:225], s[52:53], 0, v[150:151]
	s_mov_b32 m0, s49
	v_lshl_add_u64 v[226:227], s[64:65], 0, v[152:153]
	global_load_lds_dwordx4 v[224:225], off
	v_lshl_add_u64 v[224:225], s[52:53], 0, v[154:155]
	s_add_i32 m0, s49, 0x2000
	s_nop 0
	global_load_lds_dwordx4 v[224:225], off
	v_lshl_add_u64 v[224:225], s[64:65], 0, v[148:149]
	s_mov_b32 m0, s66
	s_nop 0
	global_load_lds_dwordx4 v[224:225], off
	s_mov_b32 m0, s67
	s_nop 0
	global_load_lds_dwordx4 v[226:227], off
	s_waitcnt vmcnt(8)
	s_waitcnt lgkmcnt(0)
	s_barrier
; #define PG8_STAGE(bufoff, gbase, voff) do { _Pragma("unroll") for (int _i = 0; _i < 2; ++_i) \
;         __builtin_amdgcn_global_load_lds((const unsigned*)((const char*)(gbase) + (voff)[_i]), (PG8_LAS unsigned*)(lds + (bufoff) + ldsw + _i * 8192), 16, 0, 0); } while (0)
; #define PG8_LDA(dst, b, h) do { _Pragma("unroll") for (int m = 0; m < 4; ++m) _Pragma("unroll") for (int k = 0; k < 2; ++k) dst[m][k] = *(const PG8_LAS bf16x8*)(lds + PG8_SA(b, h) + aoff + m * 2048 + k * 1024); } while (0)
; #define PG8_LDB(dst, b, h) do { _Pragma("unroll") for (int n = 0; n < 2; ++n) _Pragma("unroll") for (int k = 0; k < 2; ++k) dst[n][k] = *(const PG8_LAS bf16x8*)(lds + PG8_SB(b, h) + boff + n * 2048 + k * 1024); } while (0)
; #define PG8_MMA(ai, bj, At, Bt) do { __builtin_amdgcn_s_setprio(1); _Pragma("unroll") for (int m = 0; m < 4; ++m) _Pragma("unroll") for (int n = 0; n < 2; ++n) _Pragma("unroll") for (int k = 0; k < 2; ++k) \
;         acc[ai][bj][m][n] = __builtin_amdgcn_mfma_f32_16x16x32_bf16(Bt[n][k], At[m][k], acc[ai][bj][m][n], 0, 0, 0); __builtin_amdgcn_s_setprio(0); } while (0)
; #define PG8_WAIT_V(n) asm volatile("s_waitcnt vmcnt(" #n ")" ::: "memory")
; #define PG8_WAIT_L(n) asm volatile("s_waitcnt lgkmcnt(" #n ")" ::: "memory")
; #define PG8_BAR __builtin_amdgcn_s_barrier()
; #define PG8_SCHED __builtin_amdgcn_sched_barrier(0)
; template <class Epi, class Sched, bool ALIGN_EPI = false, bool SP2 = false>
; __device__ __forceinline__ void gemm_phase(PG8_LAS unsigned char* lds, const Gemm g, const Sched& S, const Epi& E) {
;     ...
;             PG8_WAIT_V(8); PG8_WAIT_L(0); PG8_BAR; PG8_MMA(1, 0, At, B0); PG8_MMA(1, 1, At, B1); PG8_BAR; PG8_SCHED;
;             PG8_LDB(B0, 1, 0); PG8_LDB(B1, 1, 1); PG8_SCHED; PG8_LDA(At, 1, 0); PG8_STAGE(PG8_SA(0, 1), a2 + hstep, voffA);
;             PG8_WAIT_V(8); PG8_WAIT_L(0); PG8_BAR; PG8_MMA(0, 0, At, B0); PG8_MMA(0, 1, At, B1); PG8_BAR; PG8_SCHED;
;             PG8_LDA(At, 1, 1); PG8_STAGE(PG8_SB(1, 0), b3, voffB); PG8_STAGE(PG8_SB(1, 1), b3 + hstep, voffB); PG8_STAGE(PG8_SA(1, 0), a3, voffA);
	s_setprio 1
	s_waitcnt lgkmcnt(0)
	v_mfma_f32_16x16x32_bf16 v[78:81], v[22:25], v[182:185], v[78:81]
	v_mfma_f32_16x16x32_bf16 v[74:77], v[38:41], v[182:185], v[74:77]
	v_mfma_f32_16x16x32_bf16 v[62:65], v[22:25], v[190:193], v[62:65]
	v_mfma_f32_16x16x32_bf16 v[58:61], v[38:41], v[190:193], v[58:61]
	v_mfma_f32_16x16x32_bf16 v[42:45], v[22:25], v[206:209], v[42:45]
	v_mfma_f32_16x16x32_bf16 v[34:37], v[38:41], v[206:209], v[34:37]
	v_mfma_f32_16x16x32_bf16 v[14:17], v[22:25], v[214:217], v[14:17]
	v_mfma_f32_16x16x32_bf16 v[10:13], v[38:41], v[214:217], v[10:13]
	v_mfma_f32_16x16x32_bf16 v[78:81], v[30:33], v[186:189], v[78:81]
	v_mfma_f32_16x16x32_bf16 v[74:77], v[46:49], v[186:189], v[74:77]
	v_mfma_f32_16x16x32_bf16 v[62:65], v[30:33], v[194:197], v[62:65]
	v_mfma_f32_16x16x32_bf16 v[58:61], v[46:49], v[194:197], v[58:61]
	v_mfma_f32_16x16x32_bf16 v[42:45], v[30:33], v[210:213], v[42:45]
	v_mfma_f32_16x16x32_bf16 v[34:37], v[46:49], v[210:213], v[34:37]
	v_mfma_f32_16x16x32_bf16 v[14:17], v[30:33], v[218:221], v[14:17]
	v_mfma_f32_16x16x32_bf16 v[10:13], v[46:49], v[218:221], v[10:13]
	s_setprio 0
	s_setprio 1
	v_mfma_f32_16x16x32_bf16 v[26:29], v[166:169], v[206:209], v[26:29]
	v_mfma_f32_16x16x32_bf16 v[18:21], v[174:177], v[206:209], v[18:21]
	v_mfma_f32_16x16x32_bf16 v[6:9], v[166:169], v[214:217], v[6:9]
	v_mfma_f32_16x16x32_bf16 v[2:5], v[174:177], v[214:217], v[2:5]
	v_mfma_f32_16x16x32_bf16 v[22:25], v[166:169], v[182:185], v[70:73]
	v_mfma_f32_16x16x32_bf16 v[30:33], v[174:177], v[182:185], v[66:69]
	v_mfma_f32_16x16x32_bf16 v[38:41], v[166:169], v[190:193], v[54:57]
	v_mfma_f32_16x16x32_bf16 v[46:49], v[174:177], v[190:193], v[50:53]
	v_mfma_f32_16x16x32_bf16 v[26:29], v[170:173], v[210:213], v[26:29]
	v_mfma_f32_16x16x32_bf16 v[18:21], v[178:181], v[210:213], v[18:21]
	v_mfma_f32_16x16x32_bf16 v[6:9], v[170:173], v[218:221], v[6:9]
	v_mfma_f32_16x16x32_bf16 v[2:5], v[178:181], v[218:221], v[2:5]
	v_mfma_f32_16x16x32_bf16 v[22:25], v[170:173], v[186:189], v[22:25]
	v_mfma_f32_16x16x32_bf16 v[30:33], v[178:181], v[186:189], v[30:33]
	v_mfma_f32_16x16x32_bf16 v[38:41], v[170:173], v[194:197], v[38:41]
	v_mfma_f32_16x16x32_bf16 v[46:49], v[178:181], v[194:197], v[46:49]
	s_setprio 0
	s_barrier
	s_add_i32 s49, 0, 0x18000
	s_add_i32 s54, 0, 0x1c000
	v_add_u32_e32 v70, s49, v200
	v_add_u32_e32 v178, s54, v200
	ds_read_b128 v[50:53], v70
	ds_read_b128 v[54:57], v70 offset:1024
	ds_read_b128 v[66:69], v70 offset:2048
	ds_read_b128 v[70:73], v70 offset:3072
	ds_read_b128 v[166:169], v178
	ds_read_b128 v[170:173], v178 offset:1024
	ds_read_b128 v[174:177], v178 offset:2048
	ds_read_b128 v[178:181], v178 offset:3072
	s_add_u32 s52, s64, 0x40000
	s_addc_u32 s53, s65, 0
	s_mov_b32 m0, s68
	v_lshl_add_u64 v[228:229], s[52:53], 0, v[148:149]
	ds_read_b128 v[182:185], v203 offset:32768
	ds_read_b128 v[186:189], v203 offset:33792
	ds_read_b128 v[190:193], v203 offset:34816
	ds_read_b128 v[194:197], v203 offset:35840
	ds_read_b128 v[206:209], v203 offset:36864
	ds_read_b128 v[210:213], v203 offset:37888
	ds_read_b128 v[214:217], v203 offset:38912
	ds_read_b128 v[218:221], v203 offset:39936
	global_load_lds_dwordx4 v[228:229], off
	v_lshl_add_u64 v[228:229], s[52:53], 0, v[152:153]
	s_mov_b32 m0, s69
	s_nop 0
	global_load_lds_dwordx4 v[228:229], off
	s_waitcnt vmcnt(8)
	s_waitcnt lgkmcnt(0)
	s_barrier
	s_setprio 1
	s_waitcnt lgkmcnt(0)
	v_mfma_f32_16x16x32_bf16 v[142:145], v[50:53], v[182:185], v[142:145]
	v_mfma_f32_16x16x32_bf16 v[138:141], v[66:69], v[182:185], v[138:141]
	v_mfma_f32_16x16x32_bf16 v[126:129], v[50:53], v[190:193], v[126:129]
	v_mfma_f32_16x16x32_bf16 v[122:125], v[66:69], v[190:193], v[122:125]
	v_mfma_f32_16x16x32_bf16 v[110:113], v[50:53], v[206:209], v[110:113]
	v_mfma_f32_16x16x32_bf16 v[106:109], v[66:69], v[206:209], v[106:109]
	v_mfma_f32_16x16x32_bf16 v[94:97], v[50:53], v[214:217], v[94:97]
	v_mfma_f32_16x16x32_bf16 v[90:93], v[66:69], v[214:217], v[90:93]
	v_mfma_f32_16x16x32_bf16 v[142:145], v[54:57], v[186:189], v[142:145]
	v_mfma_f32_16x16x32_bf16 v[138:141], v[70:73], v[186:189], v[138:141]
	v_mfma_f32_16x16x32_bf16 v[126:129], v[54:57], v[194:197], v[126:129]
	v_mfma_f32_16x16x32_bf16 v[122:125], v[70:73], v[194:197], v[122:125]
	v_mfma_f32_16x16x32_bf16 v[110:113], v[54:57], v[210:213], v[110:113]
	v_mfma_f32_16x16x32_bf16 v[106:109], v[70:73], v[210:213], v[106:109]
	v_mfma_f32_16x16x32_bf16 v[94:97], v[54:57], v[218:221], v[94:97]
	v_mfma_f32_16x16x32_bf16 v[90:93], v[70:73], v[218:221], v[90:93]
	s_setprio 0
	s_setprio 1
	v_mfma_f32_16x16x32_bf16 v[134:137], v[166:169], v[182:185], v[134:137]
	v_mfma_f32_16x16x32_bf16 v[130:133], v[174:177], v[182:185], v[130:133]
	v_mfma_f32_16x16x32_bf16 v[118:121], v[166:169], v[190:193], v[118:121]
	v_mfma_f32_16x16x32_bf16 v[114:117], v[174:177], v[190:193], v[114:117]
	v_mfma_f32_16x16x32_bf16 v[102:105], v[166:169], v[206:209], v[102:105]
	v_mfma_f32_16x16x32_bf16 v[98:101], v[174:177], v[206:209], v[98:101]
	v_mfma_f32_16x16x32_bf16 v[86:89], v[166:169], v[214:217], v[86:89]
	v_mfma_f32_16x16x32_bf16 v[82:85], v[174:177], v[214:217], v[82:85]
	v_mfma_f32_16x16x32_bf16 v[134:137], v[170:173], v[186:189], v[134:137]
	v_mfma_f32_16x16x32_bf16 v[130:133], v[178:181], v[186:189], v[130:133]
	v_mfma_f32_16x16x32_bf16 v[118:121], v[170:173], v[194:197], v[118:121]
	v_mfma_f32_16x16x32_bf16 v[114:117], v[178:181], v[194:197], v[114:117]
	v_mfma_f32_16x16x32_bf16 v[102:105], v[170:173], v[210:213], v[102:105]
	v_mfma_f32_16x16x32_bf16 v[98:101], v[178:181], v[210:213], v[98:101]
	v_mfma_f32_16x16x32_bf16 v[86:89], v[170:173], v[218:221], v[86:89]
	v_mfma_f32_16x16x32_bf16 v[82:85], v[178:181], v[218:221], v[82:85]
	s_setprio 0
	s_barrier
; #define PG8_STAGE(bufoff, gbase, voff) do { _Pragma("unroll") for (int _i = 0; _i < 2; ++_i) \
;         __builtin_amdgcn_global_load_lds((const unsigned*)((const char*)(gbase) + (voff)[_i]), (PG8_LAS unsigned*)(lds + (bufoff) + ldsw + _i * 8192), 16, 0, 0); } while (0)
; #define PG8_LDA(dst, b, h) do { _Pragma("unroll") for (int m = 0; m < 4; ++m) _Pragma("unroll") for (int k = 0; k < 2; ++k) dst[m][k] = *(const PG8_LAS bf16x8*)(lds + PG8_SA(b, h) + aoff + m * 2048 + k * 1024); } while (0)
; #define PG8_MMA(ai, bj, At, Bt) do { __builtin_amdgcn_s_setprio(1); _Pragma("unroll") for (int m = 0; m < 4; ++m) _Pragma("unroll") for (int n = 0; n < 2; ++n) _Pragma("unroll") for (int k = 0; k < 2; ++k) \
;         acc[ai][bj][m][n] = __builtin_amdgcn_mfma_f32_16x16x32_bf16(Bt[n][k], At[m][k], acc[ai][bj][m][n], 0, 0, 0); __builtin_amdgcn_s_setprio(0); } while (0)
; #define PG8_WAIT_V(n) asm volatile("s_waitcnt vmcnt(" #n ")" ::: "memory")
; #define PG8_WAIT_L(n) asm volatile("s_waitcnt lgkmcnt(" #n ")" ::: "memory")
; #define PG8_BAR __builtin_amdgcn_s_barrier()
; #define PG8_SCHED __builtin_amdgcn_sched_barrier(0)
; template <class Epi, class Sched, bool ALIGN_EPI = false, bool SP2 = false>
; __device__ __forceinline__ void gemm_phase(PG8_LAS unsigned char* lds, const Gemm g, const Sched& S, const Epi& E) {
;     ...
;         for (int t = 0; t < nt; t += 2) {
;     ...
;             PG8_LDA(At, 1, 1); PG8_STAGE(PG8_SB(1, 0), b3, voffB); PG8_STAGE(PG8_SB(1, 1), b3 + hstep, voffB); PG8_STAGE(PG8_SA(1, 0), a3, voffA);
;             PG8_WAIT_V(8); PG8_WAIT_L(0); PG8_BAR; PG8_MMA(1, 0, At, B0); PG8_MMA(1, 1, At, B1); PG8_BAR; PG8_SCHED;
	s_add_i32 s49, s49, s51
	v_lshl_add_u64 v[198:199], v[198:199], 0, s[30:31]
	s_mov_b32 m0, s49
	ds_read_b128 v[182:185], v203 offset:49152
	ds_read_b128 v[186:189], v203 offset:50176
	ds_read_b128 v[190:193], v203 offset:51200
	ds_read_b128 v[194:197], v203 offset:52224
	ds_read_b128 v[206:209], v203 offset:53248
	ds_read_b128 v[210:213], v203 offset:54272
	ds_read_b128 v[214:217], v203 offset:55296
	ds_read_b128 v[218:221], v203 offset:56320
	global_load_lds_dwordx4 v[198:199], off
	s_add_i32 m0, s49, 0x2000
	s_add_u32 s46, s46, 0x40080
	v_lshl_add_u64 v[198:199], v[222:223], 0, s[30:31]
	s_addc_u32 s47, s47, 0
	s_add_i32 s49, s54, s51
	global_load_lds_dwordx4 v[198:199], off
	v_lshl_add_u64 v[198:199], s[46:47], 0, v[150:151]
	s_mov_b32 m0, s49
	s_nop 0
	global_load_lds_dwordx4 v[198:199], off
	v_lshl_add_u64 v[198:199], s[46:47], 0, v[154:155]
	s_add_i32 m0, s49, 0x2000
	s_nop 0
	global_load_lds_dwordx4 v[198:199], off
	v_lshl_add_u64 v[198:199], v[224:225], 0, s[30:31]
	s_mov_b32 m0, s75
	s_nop 0
	global_load_lds_dwordx4 v[198:199], off
	v_lshl_add_u64 v[198:199], v[226:227], 0, s[30:31]
	s_mov_b32 m0, s76
	s_nop 0
	global_load_lds_dwordx4 v[198:199], off
	s_waitcnt vmcnt(8)
	s_waitcnt lgkmcnt(0)
	s_barrier
	s_setprio 1
	s_waitcnt lgkmcnt(0)
	v_mfma_f32_16x16x32_bf16 v[78:81], v[50:53], v[182:185], v[78:81]
	v_mfma_f32_16x16x32_bf16 v[74:77], v[66:69], v[182:185], v[74:77]
	v_mfma_f32_16x16x32_bf16 v[62:65], v[50:53], v[190:193], v[62:65]
	v_mfma_f32_16x16x32_bf16 v[58:61], v[66:69], v[190:193], v[58:61]
	v_mfma_f32_16x16x32_bf16 v[42:45], v[50:53], v[206:209], v[42:45]
	v_mfma_f32_16x16x32_bf16 v[34:37], v[66:69], v[206:209], v[34:37]
	v_mfma_f32_16x16x32_bf16 v[14:17], v[50:53], v[214:217], v[14:17]
	v_mfma_f32_16x16x32_bf16 v[10:13], v[66:69], v[214:217], v[10:13]
	v_mfma_f32_16x16x32_bf16 v[78:81], v[54:57], v[186:189], v[78:81]
	v_mfma_f32_16x16x32_bf16 v[74:77], v[70:73], v[186:189], v[74:77]
	v_mfma_f32_16x16x32_bf16 v[62:65], v[54:57], v[194:197], v[62:65]
	v_mfma_f32_16x16x32_bf16 v[58:61], v[70:73], v[194:197], v[58:61]
	v_mfma_f32_16x16x32_bf16 v[42:45], v[54:57], v[210:213], v[42:45]
	v_mfma_f32_16x16x32_bf16 v[34:37], v[70:73], v[210:213], v[34:37]
	v_mfma_f32_16x16x32_bf16 v[14:17], v[54:57], v[218:221], v[14:17]
	v_mfma_f32_16x16x32_bf16 v[10:13], v[70:73], v[218:221], v[10:13]
	s_setprio 0
	s_setprio 1
	v_mfma_f32_16x16x32_bf16 v[22:25], v[166:169], v[182:185], v[22:25]
	v_mfma_f32_16x16x32_bf16 v[70:73], v[170:173], v[186:189], v[22:25]
	v_mfma_f32_16x16x32_bf16 v[22:25], v[174:177], v[182:185], v[30:33]
	v_mfma_f32_16x16x32_bf16 v[66:69], v[178:181], v[186:189], v[22:25]
	v_mfma_f32_16x16x32_bf16 v[22:25], v[166:169], v[190:193], v[38:41]
	v_mfma_f32_16x16x32_bf16 v[54:57], v[170:173], v[194:197], v[22:25]
	v_mfma_f32_16x16x32_bf16 v[22:25], v[174:177], v[190:193], v[46:49]
	v_mfma_f32_16x16x32_bf16 v[50:53], v[178:181], v[194:197], v[22:25]
	v_mfma_f32_16x16x32_bf16 v[22:25], v[166:169], v[206:209], v[26:29]
	v_mfma_f32_16x16x32_bf16 v[18:21], v[174:177], v[206:209], v[18:21]
	v_mfma_f32_16x16x32_bf16 v[6:9], v[166:169], v[214:217], v[6:9]
	v_mfma_f32_16x16x32_bf16 v[2:5], v[174:177], v[214:217], v[2:5]
	v_mfma_f32_16x16x32_bf16 v[26:29], v[170:173], v[210:213], v[22:25]
	v_mfma_f32_16x16x32_bf16 v[18:21], v[178:181], v[210:213], v[18:21]
	v_mfma_f32_16x16x32_bf16 v[6:9], v[170:173], v[218:221], v[6:9]
	v_mfma_f32_16x16x32_bf16 v[2:5], v[178:181], v[218:221], v[2:5]
	s_setprio 0
	s_add_i32 s48, s48, 2
	s_add_u32 s8, s8, 0x100
	s_addc_u32 s9, s9, 0
	s_add_u32 s39, s39, 0x100
	s_addc_u32 s41, s41, 0
	s_cmp_gt_u32 s48, 13
	s_barrier
	s_cbranch_scc0 .LBB0_481
	s_and_b64 vcc, exec, s[34:35]
	s_cbranch_vccz .LBB0_484
	s_barrier

; #define PG8_STAGE(bufoff, gbase, voff) do { _Pragma("unroll") for (int _i = 0; _i < 2; ++_i) \
;         __builtin_amdgcn_global_load_lds((const unsigned*)((const char*)(gbase) + (voff)[_i]), (PG8_LAS unsigned*)(lds + (bufoff) + ldsw + _i * 8192), 16, 0, 0); } while (0)
; #define PG8_LDA(dst, b, h) do { _Pragma("unroll") for (int m = 0; m < 4; ++m) _Pragma("unroll") for (int k = 0; k < 2; ++k) dst[m][k] = *(const PG8_LAS bf16x8*)(lds + PG8_SA(b, h) + aoff + m * 2048 + k * 1024); } while (0)
; #define PG8_LDB(dst, b, h) do { _Pragma("unroll") for (int n = 0; n < 2; ++n) _Pragma("unroll") for (int k = 0; k < 2; ++k) dst[n][k] = *(const PG8_LAS bf16x8*)(lds + PG8_SB(b, h) + boff + n * 2048 + k * 1024); } while (0)
; #define PG8_MMA(ai, bj, At, Bt) do { __builtin_amdgcn_s_setprio(1); _Pragma("unroll") for (int m = 0; m < 4; ++m) _Pragma("unroll") for (int n = 0; n < 2; ++n) _Pragma("unroll") for (int k = 0; k < 2; ++k) \
;         acc[ai][bj][m][n] = __builtin_amdgcn_mfma_f32_16x16x32_bf16(Bt[n][k], At[m][k], acc[ai][bj][m][n], 0, 0, 0); __builtin_amdgcn_s_setprio(0); } while (0)
; #define PG8_WAIT_V(n) asm volatile("s_waitcnt vmcnt(" #n ")" ::: "memory")
; #define PG8_WAIT_L(n) asm volatile("s_waitcnt lgkmcnt(" #n ")" ::: "memory")
; #define PG8_BAR __builtin_amdgcn_s_barrier()
; #define PG8_SCHED __builtin_amdgcn_sched_barrier(0)
; template <class Epi, class Sched, bool ALIGN_EPI = false, bool SP2 = false>
; __device__ __forceinline__ void gemm_phase(PG8_LAS unsigned char* lds, const Gemm g, const Sched& S, const Epi& E) {
;     ...
;         for (int t = 0; t < nt; t += 2) {
;             const bool last = (t == nt - 2);
;             const char* a1 = cA + (size_t)(t + 1) * kstep;
;             const char* a2 = last ? nA : cA + (size_t)(t + 2) * kstep; const char* b2 = last ? nB : cB + (size_t)(t + 2) * kstep;
;             const char* a3 = a2 + kstep; const char* b3 = b2 + kstep;
;             if (last && has_next) S.a_ready(nxt);
;             if constexpr (SP2) {
;             PG8_LDB(B0, 0, 0); PG8_LDB(B1, 0, 1); PG8_SCHED; PG8_LDA(At, 0, 0); PG8_STAGE(PG8_SA(1, 1), a1 + hstep, voffA);
;             PG8_WAIT_V(8); PG8_WAIT_L(0); PG8_BAR; PG8_MMA(0, 0, At, B0); PG8_MMA(0, 1, At, B1); PG8_BAR; PG8_SCHED;
;             PG8_LDA(At, 0, 1); PG8_STAGE(PG8_SB(0, 0), b2, voffB); PG8_STAGE(PG8_SB(0, 1), b2 + hstep, voffB); PG8_STAGE(PG8_SA(0, 0), a2, voffA);
.LBB0_1796:
	ds_read_b128 v[130:133], v222
	ds_read_b128 v[134:137], v222 offset:1024
	ds_read_b128 v[156:159], v222 offset:2048
	ds_read_b128 v[160:163], v222 offset:3072
	ds_read_b128 v[164:167], v223
	ds_read_b128 v[168:171], v223 offset:1024
	ds_read_b128 v[172:175], v223 offset:2048
	ds_read_b128 v[176:179], v223 offset:3072
	s_add_u32 s36, s34, 0xfffc0080
	s_addc_u32 s37, s35, -1
	s_cmp_eq_u32 s67, 12
	s_cselect_b32 s39, s1, s37
	s_cselect_b32 s38, s25, s36
	s_cselect_b32 s37, s23, s66
	s_cselect_b32 s36, s31, s65
	v_lshl_add_u64 v[212:213], s[34:35], 0, v[148:149]
	s_add_i32 m0, s44, 0xc000
	ds_read_b128 v[180:183], v224
	ds_read_b128 v[184:187], v224 offset:1024
	ds_read_b128 v[188:191], v224 offset:2048
	ds_read_b128 v[192:195], v224 offset:3072
	ds_read_b128 v[196:199], v224 offset:4096
	ds_read_b128 v[200:203], v224 offset:5120
	ds_read_b128 v[204:207], v224 offset:6144
	ds_read_b128 v[208:211], v224 offset:7168
	global_load_lds_dwordx4 v[212:213], off
	v_lshl_add_u64 v[212:213], s[34:35], 0, v[150:151]
	s_add_i32 m0, s44, 0xe000
	s_nop 0
	global_load_lds_dwordx4 v[212:213], off
	s_waitcnt vmcnt(8)
	s_waitcnt lgkmcnt(0)
	s_barrier
	s_setprio 1
	s_waitcnt lgkmcnt(0)
	v_mfma_f32_16x16x32_bf16 v[126:129], v[130:133], v[180:183], v[126:129]
	v_mfma_f32_16x16x32_bf16 v[122:125], v[156:159], v[180:183], v[122:125]
	v_mfma_f32_16x16x32_bf16 v[118:121], v[130:133], v[188:191], v[118:121]
	v_mfma_f32_16x16x32_bf16 v[114:117], v[156:159], v[188:191], v[114:117]
	v_mfma_f32_16x16x32_bf16 v[110:113], v[130:133], v[196:199], v[110:113]
	v_mfma_f32_16x16x32_bf16 v[106:109], v[156:159], v[196:199], v[106:109]
	v_mfma_f32_16x16x32_bf16 v[102:105], v[130:133], v[204:207], v[102:105]
	v_mfma_f32_16x16x32_bf16 v[98:101], v[156:159], v[204:207], v[98:101]
	v_mfma_f32_16x16x32_bf16 v[126:129], v[134:137], v[184:187], v[126:129]
	v_mfma_f32_16x16x32_bf16 v[122:125], v[160:163], v[184:187], v[122:125]
	v_mfma_f32_16x16x32_bf16 v[118:121], v[134:137], v[192:195], v[118:121]
	v_mfma_f32_16x16x32_bf16 v[114:117], v[160:163], v[192:195], v[114:117]
	v_mfma_f32_16x16x32_bf16 v[110:113], v[134:137], v[200:203], v[110:113]
	v_mfma_f32_16x16x32_bf16 v[106:109], v[160:163], v[200:203], v[106:109]
	v_mfma_f32_16x16x32_bf16 v[102:105], v[134:137], v[208:211], v[102:105]
	v_mfma_f32_16x16x32_bf16 v[98:101], v[160:163], v[208:211], v[98:101]
	s_setprio 0
	s_setprio 1
	v_mfma_f32_16x16x32_bf16 v[66:69], v[164:167], v[180:183], v[66:69]
	v_mfma_f32_16x16x32_bf16 v[58:61], v[172:175], v[180:183], v[58:61]
	v_mfma_f32_16x16x32_bf16 v[54:57], v[164:167], v[188:191], v[54:57]
	v_mfma_f32_16x16x32_bf16 v[50:53], v[172:175], v[188:191], v[50:53]
	v_mfma_f32_16x16x32_bf16 v[46:49], v[164:167], v[196:199], v[46:49]
	v_mfma_f32_16x16x32_bf16 v[42:45], v[172:175], v[196:199], v[42:45]
	v_mfma_f32_16x16x32_bf16 v[38:41], v[164:167], v[204:207], v[38:41]
	v_mfma_f32_16x16x32_bf16 v[34:37], v[172:175], v[204:207], v[34:37]
	v_mfma_f32_16x16x32_bf16 v[66:69], v[168:171], v[184:187], v[66:69]
	v_mfma_f32_16x16x32_bf16 v[58:61], v[176:179], v[184:187], v[58:61]
	v_mfma_f32_16x16x32_bf16 v[54:57], v[168:171], v[192:195], v[54:57]
	v_mfma_f32_16x16x32_bf16 v[50:53], v[176:179], v[192:195], v[50:53]
	v_mfma_f32_16x16x32_bf16 v[46:49], v[168:171], v[200:203], v[46:49]
	v_mfma_f32_16x16x32_bf16 v[42:45], v[176:179], v[200:203], v[42:45]
	v_mfma_f32_16x16x32_bf16 v[38:41], v[168:171], v[208:211], v[38:41]
	v_mfma_f32_16x16x32_bf16 v[34:37], v[176:179], v[208:211], v[34:37]
	s_setprio 0
	s_barrier
	s_add_i32 s68, s59, s43
	v_lshl_add_u64 v[212:213], s[36:37], 0, v[140:141]
	s_mov_b32 m0, s68
	ds_read_b128 v[180:183], v224 offset:16384
	ds_read_b128 v[184:187], v224 offset:17408
	ds_read_b128 v[188:191], v224 offset:18432
	ds_read_b128 v[192:195], v224 offset:19456
	ds_read_b128 v[196:199], v224 offset:20480
	ds_read_b128 v[200:203], v224 offset:21504
	ds_read_b128 v[204:207], v224 offset:22528
	ds_read_b128 v[208:211], v224 offset:23552
	global_load_lds_dwordx4 v[212:213], off
	s_add_i32 m0, s68, 0x2000
	s_add_u32 s68, s36, 0x40000
	v_lshl_add_u64 v[214:215], s[36:37], 0, v[144:145]
	s_addc_u32 s69, s37, 0
	s_add_i32 s70, s62, s43
	global_load_lds_dwordx4 v[214:215], off
	v_lshl_add_u64 v[216:217], s[68:69], 0, v[140:141]
	s_mov_b32 m0, s70
	v_lshl_add_u64 v[218:219], s[38:39], 0, v[142:143]
	global_load_lds_dwordx4 v[216:217], off
	v_lshl_add_u64 v[216:217], s[68:69], 0, v[144:145]
	s_add_i32 m0, s70, 0x2000
	s_nop 0
	global_load_lds_dwordx4 v[216:217], off
	v_lshl_add_u64 v[216:217], s[38:39], 0, v[138:139]
	s_mov_b32 m0, s44
	s_nop 0
	global_load_lds_dwordx4 v[216:217], off
	s_mov_b32 m0, s33
	s_nop 0
	global_load_lds_dwordx4 v[218:219], off
	s_waitcnt vmcnt(8)
	s_waitcnt lgkmcnt(0)
	s_barrier
; #define PG8_STAGE(bufoff, gbase, voff) do { _Pragma("unroll") for (int _i = 0; _i < 2; ++_i) \
;         __builtin_amdgcn_global_load_lds((const unsigned*)((const char*)(gbase) + (voff)[_i]), (PG8_LAS unsigned*)(lds + (bufoff) + ldsw + _i * 8192), 16, 0, 0); } while (0)
; #define PG8_LDA(dst, b, h) do { _Pragma("unroll") for (int m = 0; m < 4; ++m) _Pragma("unroll") for (int k = 0; k < 2; ++k) dst[m][k] = *(const PG8_LAS bf16x8*)(lds + PG8_SA(b, h) + aoff + m * 2048 + k * 1024); } while (0)
; #define PG8_LDB(dst, b, h) do { _Pragma("unroll") for (int n = 0; n < 2; ++n) _Pragma("unroll") for (int k = 0; k < 2; ++k) dst[n][k] = *(const PG8_LAS bf16x8*)(lds + PG8_SB(b, h) + boff + n * 2048 + k * 1024); } while (0)
; #define PG8_MMA(ai, bj, At, Bt) do { __builtin_amdgcn_s_setprio(1); _Pragma("unroll") for (int m = 0; m < 4; ++m) _Pragma("unroll") for (int n = 0; n < 2; ++n) _Pragma("unroll") for (int k = 0; k < 2; ++k) \
;         acc[ai][bj][m][n] = __builtin_amdgcn_mfma_f32_16x16x32_bf16(Bt[n][k], At[m][k], acc[ai][bj][m][n], 0, 0, 0); __builtin_amdgcn_s_setprio(0); } while (0)
; #define PG8_WAIT_V(n) asm volatile("s_waitcnt vmcnt(" #n ")" ::: "memory")
; #define PG8_WAIT_L(n) asm volatile("s_waitcnt lgkmcnt(" #n ")" ::: "memory")
; #define PG8_BAR __builtin_amdgcn_s_barrier()
; #define PG8_SCHED __builtin_amdgcn_sched_barrier(0)
; template <class Epi, class Sched, bool ALIGN_EPI = false, bool SP2 = false>
; __device__ __forceinline__ void gemm_phase(PG8_LAS unsigned char* lds, const Gemm g, const Sched& S, const Epi& E) {
;     ...
;             PG8_WAIT_V(8); PG8_WAIT_L(0); PG8_BAR; PG8_MMA(1, 0, At, B0); PG8_MMA(1, 1, At, B1); PG8_BAR; PG8_SCHED;
;             PG8_LDB(B0, 1, 0); PG8_LDB(B1, 1, 1); PG8_SCHED; PG8_LDA(At, 1, 0); PG8_STAGE(PG8_SA(0, 1), a2 + hstep, voffA);
;             PG8_WAIT_V(8); PG8_WAIT_L(0); PG8_BAR; PG8_MMA(0, 0, At, B0); PG8_MMA(0, 1, At, B1); PG8_BAR; PG8_SCHED;
;             PG8_LDA(At, 1, 1); PG8_STAGE(PG8_SB(1, 0), b3, voffB); PG8_STAGE(PG8_SB(1, 1), b3 + hstep, voffB); PG8_STAGE(PG8_SA(1, 0), a3, voffA);
	s_setprio 1
	s_waitcnt lgkmcnt(0)
	v_mfma_f32_16x16x32_bf16 v[94:97], v[130:133], v[180:183], v[94:97]
	v_mfma_f32_16x16x32_bf16 v[90:93], v[156:159], v[180:183], v[90:93]
	v_mfma_f32_16x16x32_bf16 v[86:89], v[130:133], v[188:191], v[86:89]
	v_mfma_f32_16x16x32_bf16 v[82:85], v[156:159], v[188:191], v[82:85]
	v_mfma_f32_16x16x32_bf16 v[78:81], v[130:133], v[196:199], v[78:81]
	v_mfma_f32_16x16x32_bf16 v[74:77], v[156:159], v[196:199], v[74:77]
	v_mfma_f32_16x16x32_bf16 v[70:73], v[130:133], v[204:207], v[70:73]
	v_mfma_f32_16x16x32_bf16 v[62:65], v[156:159], v[204:207], v[62:65]
	v_mfma_f32_16x16x32_bf16 v[94:97], v[134:137], v[184:187], v[94:97]
	v_mfma_f32_16x16x32_bf16 v[90:93], v[160:163], v[184:187], v[90:93]
	v_mfma_f32_16x16x32_bf16 v[86:89], v[134:137], v[192:195], v[86:89]
	v_mfma_f32_16x16x32_bf16 v[82:85], v[160:163], v[192:195], v[82:85]
	v_mfma_f32_16x16x32_bf16 v[78:81], v[134:137], v[200:203], v[78:81]
	v_mfma_f32_16x16x32_bf16 v[74:77], v[160:163], v[200:203], v[74:77]
	v_mfma_f32_16x16x32_bf16 v[70:73], v[134:137], v[208:211], v[70:73]
	v_mfma_f32_16x16x32_bf16 v[62:65], v[160:163], v[208:211], v[62:65]
	s_setprio 0
	s_setprio 1
	v_mfma_f32_16x16x32_bf16 v[30:33], v[164:167], v[180:183], v[30:33]
	v_mfma_f32_16x16x32_bf16 v[26:29], v[172:175], v[180:183], v[26:29]
	v_mfma_f32_16x16x32_bf16 v[22:25], v[164:167], v[188:191], v[22:25]
	v_mfma_f32_16x16x32_bf16 v[18:21], v[172:175], v[188:191], v[18:21]
	v_mfma_f32_16x16x32_bf16 v[14:17], v[164:167], v[196:199], v[14:17]
	v_mfma_f32_16x16x32_bf16 v[10:13], v[172:175], v[196:199], v[10:13]
	v_mfma_f32_16x16x32_bf16 v[6:9], v[164:167], v[204:207], v[6:9]
	v_mfma_f32_16x16x32_bf16 v[2:5], v[172:175], v[204:207], v[2:5]
	v_mfma_f32_16x16x32_bf16 v[30:33], v[168:171], v[184:187], v[30:33]
	v_mfma_f32_16x16x32_bf16 v[26:29], v[176:179], v[184:187], v[26:29]
	v_mfma_f32_16x16x32_bf16 v[22:25], v[168:171], v[192:195], v[22:25]
	v_mfma_f32_16x16x32_bf16 v[18:21], v[176:179], v[192:195], v[18:21]
	v_mfma_f32_16x16x32_bf16 v[14:17], v[168:171], v[200:203], v[14:17]
	v_mfma_f32_16x16x32_bf16 v[10:13], v[176:179], v[200:203], v[10:13]
	v_mfma_f32_16x16x32_bf16 v[6:9], v[168:171], v[208:211], v[6:9]
	v_mfma_f32_16x16x32_bf16 v[2:5], v[176:179], v[208:211], v[2:5]
	s_setprio 0
	s_barrier
	s_add_i32 s68, 0, 0x18000
	s_add_i32 s69, 0, 0x1c000
	v_add_u32_e32 v160, s68, v221
	v_add_u32_e32 v176, s69, v221
	ds_read_b128 v[130:133], v160
	ds_read_b128 v[134:137], v160 offset:1024
	ds_read_b128 v[156:159], v160 offset:2048
	ds_read_b128 v[160:163], v160 offset:3072
	ds_read_b128 v[164:167], v176
	ds_read_b128 v[168:171], v176 offset:1024
	ds_read_b128 v[172:175], v176 offset:2048
	ds_read_b128 v[176:179], v176 offset:3072
	s_add_u32 s38, s38, 0x40000
	s_addc_u32 s39, s39, 0
	s_mov_b32 m0, s45
	v_lshl_add_u64 v[226:227], s[38:39], 0, v[138:139]
	ds_read_b128 v[180:183], v224 offset:32768
	ds_read_b128 v[184:187], v224 offset:33792
	ds_read_b128 v[188:191], v224 offset:34816
	ds_read_b128 v[192:195], v224 offset:35840
	ds_read_b128 v[196:199], v224 offset:36864
	ds_read_b128 v[200:203], v224 offset:37888
	ds_read_b128 v[204:207], v224 offset:38912
	ds_read_b128 v[208:211], v224 offset:39936
	global_load_lds_dwordx4 v[226:227], off
	v_lshl_add_u64 v[226:227], s[38:39], 0, v[142:143]
	s_mov_b32 m0, s46
	s_nop 0
	global_load_lds_dwordx4 v[226:227], off
	s_waitcnt vmcnt(8)
	s_waitcnt lgkmcnt(0)
	s_barrier
	s_setprio 1
	s_waitcnt lgkmcnt(0)
	v_mfma_f32_16x16x32_bf16 v[126:129], v[130:133], v[180:183], v[126:129]
	v_mfma_f32_16x16x32_bf16 v[122:125], v[156:159], v[180:183], v[122:125]
	v_mfma_f32_16x16x32_bf16 v[118:121], v[130:133], v[188:191], v[118:121]
	v_mfma_f32_16x16x32_bf16 v[114:117], v[156:159], v[188:191], v[114:117]
	v_mfma_f32_16x16x32_bf16 v[110:113], v[130:133], v[196:199], v[110:113]
	v_mfma_f32_16x16x32_bf16 v[106:109], v[156:159], v[196:199], v[106:109]
	v_mfma_f32_16x16x32_bf16 v[102:105], v[130:133], v[204:207], v[102:105]
	v_mfma_f32_16x16x32_bf16 v[98:101], v[156:159], v[204:207], v[98:101]
	v_mfma_f32_16x16x32_bf16 v[126:129], v[134:137], v[184:187], v[126:129]
	v_mfma_f32_16x16x32_bf16 v[122:125], v[160:163], v[184:187], v[122:125]
	v_mfma_f32_16x16x32_bf16 v[118:121], v[134:137], v[192:195], v[118:121]
	v_mfma_f32_16x16x32_bf16 v[114:117], v[160:163], v[192:195], v[114:117]
	v_mfma_f32_16x16x32_bf16 v[110:113], v[134:137], v[200:203], v[110:113]
	v_mfma_f32_16x16x32_bf16 v[106:109], v[160:163], v[200:203], v[106:109]
	v_mfma_f32_16x16x32_bf16 v[102:105], v[134:137], v[208:211], v[102:105]
	v_mfma_f32_16x16x32_bf16 v[98:101], v[160:163], v[208:211], v[98:101]
	s_setprio 0
	s_setprio 1
	v_mfma_f32_16x16x32_bf16 v[66:69], v[164:167], v[180:183], v[66:69]
	v_mfma_f32_16x16x32_bf16 v[58:61], v[172:175], v[180:183], v[58:61]
	v_mfma_f32_16x16x32_bf16 v[54:57], v[164:167], v[188:191], v[54:57]
	v_mfma_f32_16x16x32_bf16 v[50:53], v[172:175], v[188:191], v[50:53]
	v_mfma_f32_16x16x32_bf16 v[46:49], v[164:167], v[196:199], v[46:49]
	v_mfma_f32_16x16x32_bf16 v[42:45], v[172:175], v[196:199], v[42:45]
	v_mfma_f32_16x16x32_bf16 v[38:41], v[164:167], v[204:207], v[38:41]
	v_mfma_f32_16x16x32_bf16 v[34:37], v[172:175], v[204:207], v[34:37]
	v_mfma_f32_16x16x32_bf16 v[66:69], v[168:171], v[184:187], v[66:69]
	v_mfma_f32_16x16x32_bf16 v[58:61], v[176:179], v[184:187], v[58:61]
	v_mfma_f32_16x16x32_bf16 v[54:57], v[168:171], v[192:195], v[54:57]
	v_mfma_f32_16x16x32_bf16 v[50:53], v[176:179], v[192:195], v[50:53]
	v_mfma_f32_16x16x32_bf16 v[46:49], v[168:171], v[200:203], v[46:49]
	v_mfma_f32_16x16x32_bf16 v[42:45], v[176:179], v[200:203], v[42:45]
	v_mfma_f32_16x16x32_bf16 v[38:41], v[168:171], v[208:211], v[38:41]
	v_mfma_f32_16x16x32_bf16 v[34:37], v[176:179], v[208:211], v[34:37]
	s_setprio 0
	s_barrier
; #define PG8_STAGE(bufoff, gbase, voff) do { _Pragma("unroll") for (int _i = 0; _i < 2; ++_i) \
;         __builtin_amdgcn_global_load_lds((const unsigned*)((const char*)(gbase) + (voff)[_i]), (PG8_LAS unsigned*)(lds + (bufoff) + ldsw + _i * 8192), 16, 0, 0); } while (0)
; #define PG8_LDA(dst, b, h) do { _Pragma("unroll") for (int m = 0; m < 4; ++m) _Pragma("unroll") for (int k = 0; k < 2; ++k) dst[m][k] = *(const PG8_LAS bf16x8*)(lds + PG8_SA(b, h) + aoff + m * 2048 + k * 1024); } while (0)
; #define PG8_MMA(ai, bj, At, Bt) do { __builtin_amdgcn_s_setprio(1); _Pragma("unroll") for (int m = 0; m < 4; ++m) _Pragma("unroll") for (int n = 0; n < 2; ++n) _Pragma("unroll") for (int k = 0; k < 2; ++k) \
;         acc[ai][bj][m][n] = __builtin_amdgcn_mfma_f32_16x16x32_bf16(Bt[n][k], At[m][k], acc[ai][bj][m][n], 0, 0, 0); __builtin_amdgcn_s_setprio(0); } while (0)
; #define PG8_WAIT_V(n) asm volatile("s_waitcnt vmcnt(" #n ")" ::: "memory")
; #define PG8_WAIT_L(n) asm volatile("s_waitcnt lgkmcnt(" #n ")" ::: "memory")
; #define PG8_BAR __builtin_amdgcn_s_barrier()
; #define PG8_SCHED __builtin_amdgcn_sched_barrier(0)
; template <class Epi, class Sched, bool ALIGN_EPI = false, bool SP2 = false>
; __device__ __forceinline__ void gemm_phase(PG8_LAS unsigned char* lds, const Gemm g, const Sched& S, const Epi& E) {
;     ...
;         for (int t = 0; t < nt; t += 2) {
;     ...
;             PG8_LDA(At, 1, 1); PG8_STAGE(PG8_SB(1, 0), b3, voffB); PG8_STAGE(PG8_SB(1, 1), b3 + hstep, voffB); PG8_STAGE(PG8_SA(1, 0), a3, voffA);
;             PG8_WAIT_V(8); PG8_WAIT_L(0); PG8_BAR; PG8_MMA(1, 0, At, B0); PG8_MMA(1, 1, At, B1); PG8_BAR; PG8_SCHED;
	s_add_i32 s38, s68, s43
	v_lshl_add_u64 v[212:213], v[212:213], 0, s[10:11]
	s_mov_b32 m0, s38
	ds_read_b128 v[180:183], v224 offset:49152
	ds_read_b128 v[184:187], v224 offset:50176
	ds_read_b128 v[188:191], v224 offset:51200
	ds_read_b128 v[192:195], v224 offset:52224
	ds_read_b128 v[196:199], v224 offset:53248
	ds_read_b128 v[200:203], v224 offset:54272
	ds_read_b128 v[204:207], v224 offset:55296
	ds_read_b128 v[208:211], v224 offset:56320
	global_load_lds_dwordx4 v[212:213], off
	s_add_i32 m0, s38, 0x2000
	s_add_u32 s36, s36, 0x40080
	v_lshl_add_u64 v[212:213], v[214:215], 0, s[10:11]
	s_addc_u32 s37, s37, 0
	s_add_i32 s38, s69, s43
	global_load_lds_dwordx4 v[212:213], off
	v_lshl_add_u64 v[212:213], s[36:37], 0, v[140:141]
	s_mov_b32 m0, s38
	s_nop 0
	global_load_lds_dwordx4 v[212:213], off
	v_lshl_add_u64 v[212:213], s[36:37], 0, v[144:145]
	s_add_i32 m0, s38, 0x2000
	s_nop 0
	global_load_lds_dwordx4 v[212:213], off
	v_lshl_add_u64 v[212:213], v[216:217], 0, s[10:11]
	s_mov_b32 m0, s51
	s_nop 0
	global_load_lds_dwordx4 v[212:213], off
	v_lshl_add_u64 v[212:213], v[218:219], 0, s[10:11]
	s_mov_b32 m0, s52
	s_nop 0
	global_load_lds_dwordx4 v[212:213], off
	s_waitcnt vmcnt(8)
	s_waitcnt lgkmcnt(0)
	s_barrier
	s_setprio 1
	s_waitcnt lgkmcnt(0)
	v_mfma_f32_16x16x32_bf16 v[94:97], v[130:133], v[180:183], v[94:97]
	v_mfma_f32_16x16x32_bf16 v[90:93], v[156:159], v[180:183], v[90:93]
	v_mfma_f32_16x16x32_bf16 v[86:89], v[130:133], v[188:191], v[86:89]
	v_mfma_f32_16x16x32_bf16 v[82:85], v[156:159], v[188:191], v[82:85]
	v_mfma_f32_16x16x32_bf16 v[78:81], v[130:133], v[196:199], v[78:81]
	v_mfma_f32_16x16x32_bf16 v[74:77], v[156:159], v[196:199], v[74:77]
	v_mfma_f32_16x16x32_bf16 v[70:73], v[130:133], v[204:207], v[70:73]
	v_mfma_f32_16x16x32_bf16 v[62:65], v[156:159], v[204:207], v[62:65]
	v_mfma_f32_16x16x32_bf16 v[94:97], v[134:137], v[184:187], v[94:97]
	v_mfma_f32_16x16x32_bf16 v[90:93], v[160:163], v[184:187], v[90:93]
	v_mfma_f32_16x16x32_bf16 v[86:89], v[134:137], v[192:195], v[86:89]
	v_mfma_f32_16x16x32_bf16 v[82:85], v[160:163], v[192:195], v[82:85]
	v_mfma_f32_16x16x32_bf16 v[78:81], v[134:137], v[200:203], v[78:81]
	v_mfma_f32_16x16x32_bf16 v[74:77], v[160:163], v[200:203], v[74:77]
	v_mfma_f32_16x16x32_bf16 v[70:73], v[134:137], v[208:211], v[70:73]
	v_mfma_f32_16x16x32_bf16 v[62:65], v[160:163], v[208:211], v[62:65]
	s_setprio 0
	s_setprio 1
	v_mfma_f32_16x16x32_bf16 v[30:33], v[164:167], v[180:183], v[30:33]
	v_mfma_f32_16x16x32_bf16 v[26:29], v[172:175], v[180:183], v[26:29]
	v_mfma_f32_16x16x32_bf16 v[22:25], v[164:167], v[188:191], v[22:25]
	v_mfma_f32_16x16x32_bf16 v[18:21], v[172:175], v[188:191], v[18:21]
	v_mfma_f32_16x16x32_bf16 v[14:17], v[164:167], v[196:199], v[14:17]
	v_mfma_f32_16x16x32_bf16 v[10:13], v[172:175], v[196:199], v[10:13]
	v_mfma_f32_16x16x32_bf16 v[6:9], v[164:167], v[204:207], v[6:9]
	v_mfma_f32_16x16x32_bf16 v[2:5], v[172:175], v[204:207], v[2:5]
	v_mfma_f32_16x16x32_bf16 v[30:33], v[168:171], v[184:187], v[30:33]
	v_mfma_f32_16x16x32_bf16 v[26:29], v[176:179], v[184:187], v[26:29]
	v_mfma_f32_16x16x32_bf16 v[22:25], v[168:171], v[192:195], v[22:25]
	v_mfma_f32_16x16x32_bf16 v[18:21], v[176:179], v[192:195], v[18:21]
	v_mfma_f32_16x16x32_bf16 v[14:17], v[168:171], v[200:203], v[14:17]
	v_mfma_f32_16x16x32_bf16 v[10:13], v[176:179], v[200:203], v[10:13]
	v_mfma_f32_16x16x32_bf16 v[6:9], v[168:171], v[208:211], v[6:9]
	v_mfma_f32_16x16x32_bf16 v[2:5], v[176:179], v[208:211], v[2:5]
	s_setprio 0
	s_add_i32 s67, s67, 2
	s_add_u32 s34, s34, 0x100
	s_addc_u32 s35, s35, 0
	s_add_u32 s65, s65, 0x100
	s_addc_u32 s66, s66, 0
	s_cmp_gt_u32 s67, 13
	s_barrier
	s_cbranch_scc0 .LBB0_1796
	s_and_b64 vcc, exec, s[12:13]
	s_cbranch_vccz .LBB0_1799
	s_barrier

; #define PG8_STAGE(bufoff, gbase, voff) do { _Pragma("unroll") for (int _i = 0; _i < 2; ++_i) \
;         __builtin_amdgcn_global_load_lds((const unsigned*)((const char*)(gbase) + (voff)[_i]), (PG8_LAS unsigned*)(lds + (bufoff) + ldsw + _i * 8192), 16, 0, 0); } while (0)
; #define PG8_LDA(dst, b, h) do { _Pragma("unroll") for (int m = 0; m < 4; ++m) _Pragma("unroll") for (int k = 0; k < 2; ++k) dst[m][k] = *(const PG8_LAS bf16x8*)(lds + PG8_SA(b, h) + aoff + m * 2048 + k * 1024); } while (0)
; #define PG8_LDB(dst, b, h) do { _Pragma("unroll") for (int n = 0; n < 2; ++n) _Pragma("unroll") for (int k = 0; k < 2; ++k) dst[n][k] = *(const PG8_LAS bf16x8*)(lds + PG8_SB(b, h) + boff + n * 2048 + k * 1024); } while (0)
; #define PG8_MMA(ai, bj, At, Bt) do { __builtin_amdgcn_s_setprio(1); _Pragma("unroll") for (int m = 0; m < 4; ++m) _Pragma("unroll") for (int n = 0; n < 2; ++n) _Pragma("unroll") for (int k = 0; k < 2; ++k) \
;         acc[ai][bj][m][n] = __builtin_amdgcn_mfma_f32_16x16x32_bf16(Bt[n][k], At[m][k], acc[ai][bj][m][n], 0, 0, 0); __builtin_amdgcn_s_setprio(0); } while (0)
; #define PG8_WAIT_V(n) asm volatile("s_waitcnt vmcnt(" #n ")" ::: "memory")
; #define PG8_WAIT_L(n) asm volatile("s_waitcnt lgkmcnt(" #n ")" ::: "memory")
; #define PG8_BAR __builtin_amdgcn_s_barrier()
; #define PG8_SCHED __builtin_amdgcn_sched_barrier(0)
; template <class Epi, class Sched, bool ALIGN_EPI = false, bool SP2 = false>
; __device__ __forceinline__ void gemm_phase(PG8_LAS unsigned char* lds, const Gemm g, const Sched& S, const Epi& E) {
;     ...
;         for (int t = 0; t < nt; t += 2) {
;             const bool last = (t == nt - 2);
;             const char* a1 = cA + (size_t)(t + 1) * kstep;
;             const char* a2 = last ? nA : cA + (size_t)(t + 2) * kstep; const char* b2 = last ? nB : cB + (size_t)(t + 2) * kstep;
;             const char* a3 = a2 + kstep; const char* b3 = b2 + kstep;
;             if (last && has_next) S.a_ready(nxt);
;             if constexpr (SP2) {
;             PG8_LDB(B0, 0, 0); PG8_LDB(B1, 0, 1); PG8_SCHED; PG8_LDA(At, 0, 0); PG8_STAGE(PG8_SA(1, 1), a1 + hstep, voffA);
;             PG8_WAIT_V(8); PG8_WAIT_L(0); PG8_BAR; PG8_MMA(0, 0, At, B0); PG8_MMA(0, 1, At, B1); PG8_BAR; PG8_SCHED;
;             PG8_LDA(At, 0, 1); PG8_STAGE(PG8_SB(0, 0), b2, voffB); PG8_STAGE(PG8_SB(0, 1), b2 + hstep, voffB); PG8_STAGE(PG8_SA(0, 0), a2, voffA);
.LBB0_1895:
	ds_read_b128 v[130:133], v181
	ds_read_b128 v[134:137], v181 offset:1024
	ds_read_b128 v[138:141], v181 offset:2048
	ds_read_b128 v[142:145], v181 offset:3072
	ds_read_b128 v[164:167], v185
	ds_read_b128 v[172:175], v185 offset:1024
	ds_read_b128 v[192:195], v185 offset:2048
	ds_read_b128 v[196:199], v185 offset:3072
	s_add_u32 s30, s6, 0xfffc0080
	s_addc_u32 s31, s7, -1
	s_cmp_eq_u32 s63, 12
	s_cselect_b32 s35, s25, s31
	s_cselect_b32 s34, s55, s30
	s_cselect_b32 s31, s23, s62
	s_cselect_b32 s30, s58, s59
	v_lshl_add_u64 v[168:169], s[6:7], 0, v[156:157]
	s_add_i32 m0, s37, 0xc000
	ds_read_b128 v[200:203], v189
	ds_read_b128 v[204:207], v189 offset:1024
	ds_read_b128 v[208:211], v189 offset:2048
	ds_read_b128 v[212:215], v189 offset:3072
	ds_read_b128 v[216:219], v189 offset:4096
	ds_read_b128 v[220:223], v189 offset:5120
	ds_read_b128 v[224:227], v189 offset:6144
	ds_read_b128 v[228:231], v189 offset:7168
	global_load_lds_dwordx4 v[168:169], off
	v_lshl_add_u64 v[168:169], s[6:7], 0, v[158:159]
	s_add_i32 m0, s37, 0xe000
	s_nop 0
	global_load_lds_dwordx4 v[168:169], off
	s_waitcnt vmcnt(8)
	s_waitcnt lgkmcnt(0)
	s_barrier
	s_setprio 1
	s_waitcnt lgkmcnt(0)
	v_mfma_f32_16x16x32_bf16 v[126:129], v[130:133], v[200:203], v[126:129]
	v_mfma_f32_16x16x32_bf16 v[122:125], v[138:141], v[200:203], v[122:125]
	v_mfma_f32_16x16x32_bf16 v[110:113], v[130:133], v[208:211], v[110:113]
	v_mfma_f32_16x16x32_bf16 v[106:109], v[138:141], v[208:211], v[106:109]
	v_mfma_f32_16x16x32_bf16 v[94:97], v[130:133], v[216:219], v[94:97]
	v_mfma_f32_16x16x32_bf16 v[90:93], v[138:141], v[216:219], v[90:93]
	v_mfma_f32_16x16x32_bf16 v[78:81], v[130:133], v[224:227], v[78:81]
	v_mfma_f32_16x16x32_bf16 v[74:77], v[138:141], v[224:227], v[74:77]
	v_mfma_f32_16x16x32_bf16 v[126:129], v[134:137], v[204:207], v[126:129]
	v_mfma_f32_16x16x32_bf16 v[122:125], v[142:145], v[204:207], v[122:125]
	v_mfma_f32_16x16x32_bf16 v[110:113], v[134:137], v[212:215], v[110:113]
	v_mfma_f32_16x16x32_bf16 v[106:109], v[142:145], v[212:215], v[106:109]
	v_mfma_f32_16x16x32_bf16 v[94:97], v[134:137], v[220:223], v[94:97]
	v_mfma_f32_16x16x32_bf16 v[90:93], v[142:145], v[220:223], v[90:93]
	v_mfma_f32_16x16x32_bf16 v[78:81], v[134:137], v[228:231], v[78:81]
	v_mfma_f32_16x16x32_bf16 v[74:77], v[142:145], v[228:231], v[74:77]
	s_setprio 0
	s_setprio 1
	v_mfma_f32_16x16x32_bf16 v[118:121], v[164:167], v[200:203], v[118:121]
	v_mfma_f32_16x16x32_bf16 v[114:117], v[192:195], v[200:203], v[114:117]
	v_mfma_f32_16x16x32_bf16 v[102:105], v[164:167], v[208:211], v[102:105]
	v_mfma_f32_16x16x32_bf16 v[98:101], v[192:195], v[208:211], v[98:101]
	v_mfma_f32_16x16x32_bf16 v[86:89], v[164:167], v[216:219], v[86:89]
	v_mfma_f32_16x16x32_bf16 v[82:85], v[192:195], v[216:219], v[82:85]
	v_mfma_f32_16x16x32_bf16 v[70:73], v[164:167], v[224:227], v[70:73]
	v_mfma_f32_16x16x32_bf16 v[66:69], v[192:195], v[224:227], v[66:69]
	v_mfma_f32_16x16x32_bf16 v[118:121], v[172:175], v[204:207], v[118:121]
	v_mfma_f32_16x16x32_bf16 v[114:117], v[196:199], v[204:207], v[114:117]
	v_mfma_f32_16x16x32_bf16 v[102:105], v[172:175], v[212:215], v[102:105]
	v_mfma_f32_16x16x32_bf16 v[98:101], v[196:199], v[212:215], v[98:101]
	v_mfma_f32_16x16x32_bf16 v[86:89], v[172:175], v[220:223], v[86:89]
	v_mfma_f32_16x16x32_bf16 v[82:85], v[196:199], v[220:223], v[82:85]
	v_mfma_f32_16x16x32_bf16 v[70:73], v[172:175], v[228:231], v[70:73]
	v_mfma_f32_16x16x32_bf16 v[66:69], v[196:199], v[228:231], v[66:69]
	s_setprio 0
	s_barrier
	s_add_i32 s64, s49, s21
	v_lshl_add_u64 v[168:169], s[30:31], 0, v[152:153]
	s_mov_b32 m0, s64
	ds_read_b128 v[200:203], v189 offset:16384
	ds_read_b128 v[204:207], v189 offset:17408
	ds_read_b128 v[208:211], v189 offset:18432
	ds_read_b128 v[212:215], v189 offset:19456
	ds_read_b128 v[216:219], v189 offset:20480
	ds_read_b128 v[220:223], v189 offset:21504
	ds_read_b128 v[224:227], v189 offset:22528
	ds_read_b128 v[228:231], v189 offset:23552
	global_load_lds_dwordx4 v[168:169], off
	s_add_i32 m0, s64, 0x2000
	s_add_u32 s64, s30, 0x40000
	v_lshl_add_u64 v[178:179], s[30:31], 0, v[148:149]
	s_addc_u32 s65, s31, 0
	s_add_i32 s66, s51, s21
	global_load_lds_dwordx4 v[178:179], off
	v_lshl_add_u64 v[182:183], s[64:65], 0, v[152:153]
	s_mov_b32 m0, s66
	v_lshl_add_u64 v[186:187], s[34:35], 0, v[150:151]
	global_load_lds_dwordx4 v[182:183], off
	v_lshl_add_u64 v[182:183], s[64:65], 0, v[148:149]
	s_add_i32 m0, s66, 0x2000
	s_nop 0
	global_load_lds_dwordx4 v[182:183], off
	v_lshl_add_u64 v[182:183], s[34:35], 0, v[154:155]
	s_mov_b32 m0, s37
	s_nop 0
	global_load_lds_dwordx4 v[182:183], off
	s_mov_b32 m0, s38
	s_nop 0
	global_load_lds_dwordx4 v[186:187], off
	s_waitcnt vmcnt(8)
	s_waitcnt lgkmcnt(0)
	s_barrier
; #define PG8_STAGE(bufoff, gbase, voff) do { _Pragma("unroll") for (int _i = 0; _i < 2; ++_i) \
;         __builtin_amdgcn_global_load_lds((const unsigned*)((const char*)(gbase) + (voff)[_i]), (PG8_LAS unsigned*)(lds + (bufoff) + ldsw + _i * 8192), 16, 0, 0); } while (0)
; #define PG8_LDA(dst, b, h) do { _Pragma("unroll") for (int m = 0; m < 4; ++m) _Pragma("unroll") for (int k = 0; k < 2; ++k) dst[m][k] = *(const PG8_LAS bf16x8*)(lds + PG8_SA(b, h) + aoff + m * 2048 + k * 1024); } while (0)
; #define PG8_LDB(dst, b, h) do { _Pragma("unroll") for (int n = 0; n < 2; ++n) _Pragma("unroll") for (int k = 0; k < 2; ++k) dst[n][k] = *(const PG8_LAS bf16x8*)(lds + PG8_SB(b, h) + boff + n * 2048 + k * 1024); } while (0)
; #define PG8_MMA(ai, bj, At, Bt) do { __builtin_amdgcn_s_setprio(1); _Pragma("unroll") for (int m = 0; m < 4; ++m) _Pragma("unroll") for (int n = 0; n < 2; ++n) _Pragma("unroll") for (int k = 0; k < 2; ++k) \
;         acc[ai][bj][m][n] = __builtin_amdgcn_mfma_f32_16x16x32_bf16(Bt[n][k], At[m][k], acc[ai][bj][m][n], 0, 0, 0); __builtin_amdgcn_s_setprio(0); } while (0)
; #define PG8_WAIT_V(n) asm volatile("s_waitcnt vmcnt(" #n ")" ::: "memory")
; #define PG8_WAIT_L(n) asm volatile("s_waitcnt lgkmcnt(" #n ")" ::: "memory")
; #define PG8_BAR __builtin_amdgcn_s_barrier()
; #define PG8_SCHED __builtin_amdgcn_sched_barrier(0)
; template <class Epi, class Sched, bool ALIGN_EPI = false, bool SP2 = false>
; __device__ __forceinline__ void gemm_phase(PG8_LAS unsigned char* lds, const Gemm g, const Sched& S, const Epi& E) {
;     ...
;             PG8_WAIT_V(8); PG8_WAIT_L(0); PG8_BAR; PG8_MMA(1, 0, At, B0); PG8_MMA(1, 1, At, B1); PG8_BAR; PG8_SCHED;
;             PG8_LDB(B0, 1, 0); PG8_LDB(B1, 1, 1); PG8_SCHED; PG8_LDA(At, 1, 0); PG8_STAGE(PG8_SA(0, 1), a2 + hstep, voffA);
;             PG8_WAIT_V(8); PG8_WAIT_L(0); PG8_BAR; PG8_MMA(0, 0, At, B0); PG8_MMA(0, 1, At, B1); PG8_BAR; PG8_SCHED;
;             PG8_LDA(At, 1, 1); PG8_STAGE(PG8_SB(1, 0), b3, voffB); PG8_STAGE(PG8_SB(1, 1), b3 + hstep, voffB); PG8_STAGE(PG8_SA(1, 0), a3, voffA);
	s_setprio 1
	s_waitcnt lgkmcnt(0)
	v_mfma_f32_16x16x32_bf16 v[62:65], v[130:133], v[200:203], v[62:65]
	v_mfma_f32_16x16x32_bf16 v[58:61], v[138:141], v[200:203], v[58:61]
	v_mfma_f32_16x16x32_bf16 v[46:49], v[130:133], v[208:211], v[46:49]
	v_mfma_f32_16x16x32_bf16 v[42:45], v[138:141], v[208:211], v[42:45]
	v_mfma_f32_16x16x32_bf16 v[30:33], v[130:133], v[216:219], v[30:33]
	v_mfma_f32_16x16x32_bf16 v[26:29], v[138:141], v[216:219], v[26:29]
	v_mfma_f32_16x16x32_bf16 v[14:17], v[130:133], v[224:227], v[14:17]
	v_mfma_f32_16x16x32_bf16 v[10:13], v[138:141], v[224:227], v[10:13]
	v_mfma_f32_16x16x32_bf16 v[62:65], v[134:137], v[204:207], v[62:65]
	v_mfma_f32_16x16x32_bf16 v[58:61], v[142:145], v[204:207], v[58:61]
	v_mfma_f32_16x16x32_bf16 v[46:49], v[134:137], v[212:215], v[46:49]
	v_mfma_f32_16x16x32_bf16 v[42:45], v[142:145], v[212:215], v[42:45]
	v_mfma_f32_16x16x32_bf16 v[30:33], v[134:137], v[220:223], v[30:33]
	v_mfma_f32_16x16x32_bf16 v[26:29], v[142:145], v[220:223], v[26:29]
	v_mfma_f32_16x16x32_bf16 v[14:17], v[134:137], v[228:231], v[14:17]
	v_mfma_f32_16x16x32_bf16 v[10:13], v[142:145], v[228:231], v[10:13]
	s_setprio 0
	s_setprio 1
	v_mfma_f32_16x16x32_bf16 v[54:57], v[164:167], v[200:203], v[54:57]
	v_mfma_f32_16x16x32_bf16 v[50:53], v[192:195], v[200:203], v[50:53]
	v_mfma_f32_16x16x32_bf16 v[38:41], v[164:167], v[208:211], v[38:41]
	v_mfma_f32_16x16x32_bf16 v[34:37], v[192:195], v[208:211], v[34:37]
	v_mfma_f32_16x16x32_bf16 v[22:25], v[164:167], v[216:219], v[22:25]
	v_mfma_f32_16x16x32_bf16 v[18:21], v[192:195], v[216:219], v[18:21]
	v_mfma_f32_16x16x32_bf16 v[6:9], v[164:167], v[224:227], v[6:9]
	v_mfma_f32_16x16x32_bf16 v[2:5], v[192:195], v[224:227], v[2:5]
	v_mfma_f32_16x16x32_bf16 v[54:57], v[172:175], v[204:207], v[54:57]
	v_mfma_f32_16x16x32_bf16 v[50:53], v[196:199], v[204:207], v[50:53]
	v_mfma_f32_16x16x32_bf16 v[38:41], v[172:175], v[212:215], v[38:41]
	v_mfma_f32_16x16x32_bf16 v[34:37], v[196:199], v[212:215], v[34:37]
	v_mfma_f32_16x16x32_bf16 v[22:25], v[172:175], v[220:223], v[22:25]
	v_mfma_f32_16x16x32_bf16 v[18:21], v[196:199], v[220:223], v[18:21]
	v_mfma_f32_16x16x32_bf16 v[6:9], v[172:175], v[228:231], v[6:9]
	v_mfma_f32_16x16x32_bf16 v[2:5], v[196:199], v[228:231], v[2:5]
	s_setprio 0
	s_barrier
	s_add_i32 s64, 0, 0x18000
	s_add_i32 s65, 0, 0x1c000
	v_add_u32_e32 v142, s64, v177
	v_add_u32_e32 v170, s65, v177
	ds_read_b128 v[130:133], v142
	ds_read_b128 v[134:137], v142 offset:1024
	ds_read_b128 v[138:141], v142 offset:2048
	ds_read_b128 v[142:145], v142 offset:3072
	ds_read_b128 v[164:167], v170
	ds_read_b128 v[172:175], v170 offset:1024
	ds_read_b128 v[192:195], v170 offset:2048
	ds_read_b128 v[196:199], v170 offset:3072
	s_add_u32 s34, s34, 0x40000
	s_addc_u32 s35, s35, 0
	s_mov_b32 m0, s39
	v_lshl_add_u64 v[232:233], s[34:35], 0, v[154:155]
	ds_read_b128 v[200:203], v189 offset:32768
	ds_read_b128 v[204:207], v189 offset:33792
	ds_read_b128 v[208:211], v189 offset:34816
	ds_read_b128 v[212:215], v189 offset:35840
	ds_read_b128 v[216:219], v189 offset:36864
	ds_read_b128 v[220:223], v189 offset:37888
	ds_read_b128 v[224:227], v189 offset:38912
	ds_read_b128 v[228:231], v189 offset:39936
	global_load_lds_dwordx4 v[232:233], off
	v_lshl_add_u64 v[232:233], s[34:35], 0, v[150:151]
	s_mov_b32 m0, s40
	s_nop 0
	global_load_lds_dwordx4 v[232:233], off
	s_waitcnt vmcnt(8)
	s_waitcnt lgkmcnt(0)
	s_barrier
	s_setprio 1
	s_waitcnt lgkmcnt(0)
	v_mfma_f32_16x16x32_bf16 v[126:129], v[130:133], v[200:203], v[126:129]
	v_mfma_f32_16x16x32_bf16 v[122:125], v[138:141], v[200:203], v[122:125]
	v_mfma_f32_16x16x32_bf16 v[110:113], v[130:133], v[208:211], v[110:113]
	v_mfma_f32_16x16x32_bf16 v[106:109], v[138:141], v[208:211], v[106:109]
	v_mfma_f32_16x16x32_bf16 v[94:97], v[130:133], v[216:219], v[94:97]
	v_mfma_f32_16x16x32_bf16 v[90:93], v[138:141], v[216:219], v[90:93]
	v_mfma_f32_16x16x32_bf16 v[78:81], v[130:133], v[224:227], v[78:81]
	v_mfma_f32_16x16x32_bf16 v[74:77], v[138:141], v[224:227], v[74:77]
	v_mfma_f32_16x16x32_bf16 v[126:129], v[134:137], v[204:207], v[126:129]
	v_mfma_f32_16x16x32_bf16 v[122:125], v[142:145], v[204:207], v[122:125]
	v_mfma_f32_16x16x32_bf16 v[110:113], v[134:137], v[212:215], v[110:113]
	v_mfma_f32_16x16x32_bf16 v[106:109], v[142:145], v[212:215], v[106:109]
	v_mfma_f32_16x16x32_bf16 v[94:97], v[134:137], v[220:223], v[94:97]
	v_mfma_f32_16x16x32_bf16 v[90:93], v[142:145], v[220:223], v[90:93]
	v_mfma_f32_16x16x32_bf16 v[78:81], v[134:137], v[228:231], v[78:81]
	v_mfma_f32_16x16x32_bf16 v[74:77], v[142:145], v[228:231], v[74:77]
	s_setprio 0
	s_setprio 1
	v_mfma_f32_16x16x32_bf16 v[118:121], v[164:167], v[200:203], v[118:121]
	v_mfma_f32_16x16x32_bf16 v[114:117], v[192:195], v[200:203], v[114:117]
	v_mfma_f32_16x16x32_bf16 v[102:105], v[164:167], v[208:211], v[102:105]
	v_mfma_f32_16x16x32_bf16 v[98:101], v[192:195], v[208:211], v[98:101]
	v_mfma_f32_16x16x32_bf16 v[86:89], v[164:167], v[216:219], v[86:89]
	v_mfma_f32_16x16x32_bf16 v[82:85], v[192:195], v[216:219], v[82:85]
	v_mfma_f32_16x16x32_bf16 v[70:73], v[164:167], v[224:227], v[70:73]
	v_mfma_f32_16x16x32_bf16 v[66:69], v[192:195], v[224:227], v[66:69]
	v_mfma_f32_16x16x32_bf16 v[118:121], v[172:175], v[204:207], v[118:121]
	v_mfma_f32_16x16x32_bf16 v[114:117], v[196:199], v[204:207], v[114:117]
	v_mfma_f32_16x16x32_bf16 v[102:105], v[172:175], v[212:215], v[102:105]
	v_mfma_f32_16x16x32_bf16 v[98:101], v[196:199], v[212:215], v[98:101]
	v_mfma_f32_16x16x32_bf16 v[86:89], v[172:175], v[220:223], v[86:89]
	v_mfma_f32_16x16x32_bf16 v[82:85], v[196:199], v[220:223], v[82:85]
	v_mfma_f32_16x16x32_bf16 v[70:73], v[172:175], v[228:231], v[70:73]
	v_mfma_f32_16x16x32_bf16 v[66:69], v[196:199], v[228:231], v[66:69]
	s_setprio 0
	s_barrier
; #define PG8_STAGE(bufoff, gbase, voff) do { _Pragma("unroll") for (int _i = 0; _i < 2; ++_i) \
;         __builtin_amdgcn_global_load_lds((const unsigned*)((const char*)(gbase) + (voff)[_i]), (PG8_LAS unsigned*)(lds + (bufoff) + ldsw + _i * 8192), 16, 0, 0); } while (0)
; #define PG8_LDA(dst, b, h) do { _Pragma("unroll") for (int m = 0; m < 4; ++m) _Pragma("unroll") for (int k = 0; k < 2; ++k) dst[m][k] = *(const PG8_LAS bf16x8*)(lds + PG8_SA(b, h) + aoff + m * 2048 + k * 1024); } while (0)
; #define PG8_MMA(ai, bj, At, Bt) do { __builtin_amdgcn_s_setprio(1); _Pragma("unroll") for (int m = 0; m < 4; ++m) _Pragma("unroll") for (int n = 0; n < 2; ++n) _Pragma("unroll") for (int k = 0; k < 2; ++k) \
;         acc[ai][bj][m][n] = __builtin_amdgcn_mfma_f32_16x16x32_bf16(Bt[n][k], At[m][k], acc[ai][bj][m][n], 0, 0, 0); __builtin_amdgcn_s_setprio(0); } while (0)
; #define PG8_WAIT_V(n) asm volatile("s_waitcnt vmcnt(" #n ")" ::: "memory")
; #define PG8_WAIT_L(n) asm volatile("s_waitcnt lgkmcnt(" #n ")" ::: "memory")
; #define PG8_BAR __builtin_amdgcn_s_barrier()
; #define PG8_SCHED __builtin_amdgcn_sched_barrier(0)
; template <class Epi, class Sched, bool ALIGN_EPI = false, bool SP2 = false>
; __device__ __forceinline__ void gemm_phase(PG8_LAS unsigned char* lds, const Gemm g, const Sched& S, const Epi& E) {
;     ...
;         for (int t = 0; t < nt; t += 2) {
;     ...
;             PG8_LDA(At, 1, 1); PG8_STAGE(PG8_SB(1, 0), b3, voffB); PG8_STAGE(PG8_SB(1, 1), b3 + hstep, voffB); PG8_STAGE(PG8_SA(1, 0), a3, voffA);
;             PG8_WAIT_V(8); PG8_WAIT_L(0); PG8_BAR; PG8_MMA(1, 0, At, B0); PG8_MMA(1, 1, At, B1); PG8_BAR; PG8_SCHED;
	s_add_i32 s34, s64, s21
	v_lshl_add_u64 v[168:169], v[168:169], 0, s[14:15]
	s_mov_b32 m0, s34
	ds_read_b128 v[200:203], v189 offset:49152
	ds_read_b128 v[204:207], v189 offset:50176
	ds_read_b128 v[208:211], v189 offset:51200
	ds_read_b128 v[212:215], v189 offset:52224
	ds_read_b128 v[216:219], v189 offset:53248
	ds_read_b128 v[220:223], v189 offset:54272
	ds_read_b128 v[224:227], v189 offset:55296
	ds_read_b128 v[228:231], v189 offset:56320
	global_load_lds_dwordx4 v[168:169], off
	s_add_i32 m0, s34, 0x2000
	s_add_u32 s30, s30, 0x40080
	v_lshl_add_u64 v[168:169], v[178:179], 0, s[14:15]
	s_addc_u32 s31, s31, 0
	s_add_i32 s34, s65, s21
	global_load_lds_dwordx4 v[168:169], off
	v_lshl_add_u64 v[168:169], s[30:31], 0, v[152:153]
	s_mov_b32 m0, s34
	s_nop 0
	global_load_lds_dwordx4 v[168:169], off
	v_lshl_add_u64 v[168:169], s[30:31], 0, v[148:149]
	s_add_i32 m0, s34, 0x2000
	s_nop 0
	global_load_lds_dwordx4 v[168:169], off
	v_lshl_add_u64 v[168:169], v[182:183], 0, s[14:15]
	s_mov_b32 m0, s46
	s_nop 0
	global_load_lds_dwordx4 v[168:169], off
	v_lshl_add_u64 v[168:169], v[186:187], 0, s[14:15]
	s_mov_b32 m0, s47
	s_nop 0
	global_load_lds_dwordx4 v[168:169], off
	s_waitcnt vmcnt(8)
	s_waitcnt lgkmcnt(0)
	s_barrier
	s_setprio 1
	s_waitcnt lgkmcnt(0)
	v_mfma_f32_16x16x32_bf16 v[62:65], v[130:133], v[200:203], v[62:65]
	v_mfma_f32_16x16x32_bf16 v[58:61], v[138:141], v[200:203], v[58:61]
	v_mfma_f32_16x16x32_bf16 v[46:49], v[130:133], v[208:211], v[46:49]
	v_mfma_f32_16x16x32_bf16 v[42:45], v[138:141], v[208:211], v[42:45]
	v_mfma_f32_16x16x32_bf16 v[30:33], v[130:133], v[216:219], v[30:33]
	v_mfma_f32_16x16x32_bf16 v[26:29], v[138:141], v[216:219], v[26:29]
	v_mfma_f32_16x16x32_bf16 v[14:17], v[130:133], v[224:227], v[14:17]
	v_mfma_f32_16x16x32_bf16 v[10:13], v[138:141], v[224:227], v[10:13]
	v_mfma_f32_16x16x32_bf16 v[62:65], v[134:137], v[204:207], v[62:65]
	v_mfma_f32_16x16x32_bf16 v[58:61], v[142:145], v[204:207], v[58:61]
	v_mfma_f32_16x16x32_bf16 v[46:49], v[134:137], v[212:215], v[46:49]
	v_mfma_f32_16x16x32_bf16 v[42:45], v[142:145], v[212:215], v[42:45]
	v_mfma_f32_16x16x32_bf16 v[30:33], v[134:137], v[220:223], v[30:33]
	v_mfma_f32_16x16x32_bf16 v[26:29], v[142:145], v[220:223], v[26:29]
	v_mfma_f32_16x16x32_bf16 v[14:17], v[134:137], v[228:231], v[14:17]
	v_mfma_f32_16x16x32_bf16 v[10:13], v[142:145], v[228:231], v[10:13]
	s_setprio 0
	s_setprio 1
	v_mfma_f32_16x16x32_bf16 v[54:57], v[164:167], v[200:203], v[54:57]
	v_mfma_f32_16x16x32_bf16 v[50:53], v[192:195], v[200:203], v[50:53]
	v_mfma_f32_16x16x32_bf16 v[38:41], v[164:167], v[208:211], v[38:41]
	v_mfma_f32_16x16x32_bf16 v[34:37], v[192:195], v[208:211], v[34:37]
	v_mfma_f32_16x16x32_bf16 v[22:25], v[164:167], v[216:219], v[22:25]
	v_mfma_f32_16x16x32_bf16 v[18:21], v[192:195], v[216:219], v[18:21]
	v_mfma_f32_16x16x32_bf16 v[6:9], v[164:167], v[224:227], v[6:9]
	v_mfma_f32_16x16x32_bf16 v[2:5], v[192:195], v[224:227], v[2:5]
	v_mfma_f32_16x16x32_bf16 v[54:57], v[172:175], v[204:207], v[54:57]
	v_mfma_f32_16x16x32_bf16 v[50:53], v[196:199], v[204:207], v[50:53]
	v_mfma_f32_16x16x32_bf16 v[38:41], v[172:175], v[212:215], v[38:41]
	v_mfma_f32_16x16x32_bf16 v[34:37], v[196:199], v[212:215], v[34:37]
	v_mfma_f32_16x16x32_bf16 v[22:25], v[172:175], v[220:223], v[22:25]
	v_mfma_f32_16x16x32_bf16 v[18:21], v[196:199], v[220:223], v[18:21]
	v_mfma_f32_16x16x32_bf16 v[6:9], v[172:175], v[228:231], v[6:9]
	v_mfma_f32_16x16x32_bf16 v[2:5], v[196:199], v[228:231], v[2:5]
	s_setprio 0
	s_add_i32 s63, s63, 2
	s_add_u32 s6, s6, 0x100
	s_addc_u32 s7, s7, 0
	s_add_u32 s59, s59, 0x100
	s_addc_u32 s62, s62, 0
	s_cmp_gt_u32 s63, 13
	s_barrier
	s_cbranch_scc0 .LBB0_1895
	s_and_b64 vcc, exec, s[16:17]
	s_cbranch_vccz .LBB0_1898
	s_barrier

; #define PG8_STAGE(bufoff, gbase, voff) do { _Pragma("unroll") for (int _i = 0; _i < 2; ++_i) \
;         __builtin_amdgcn_global_load_lds((const unsigned*)((const char*)(gbase) + (voff)[_i]), (PG8_LAS unsigned*)(lds + (bufoff) + ldsw + _i * 8192), 16, 0, 0); } while (0)
; #define PG8_LDA(dst, b, h) do { _Pragma("unroll") for (int m = 0; m < 4; ++m) _Pragma("unroll") for (int k = 0; k < 2; ++k) dst[m][k] = *(const PG8_LAS bf16x8*)(lds + PG8_SA(b, h) + aoff + m * 2048 + k * 1024); } while (0)
; #define PG8_LDB(dst, b, h) do { _Pragma("unroll") for (int n = 0; n < 2; ++n) _Pragma("unroll") for (int k = 0; k < 2; ++k) dst[n][k] = *(const PG8_LAS bf16x8*)(lds + PG8_SB(b, h) + boff + n * 2048 + k * 1024); } while (0)
; #define PG8_MMA(ai, bj, At, Bt) do { __builtin_amdgcn_s_setprio(1); _Pragma("unroll") for (int m = 0; m < 4; ++m) _Pragma("unroll") for (int n = 0; n < 2; ++n) _Pragma("unroll") for (int k = 0; k < 2; ++k) \
;         acc[ai][bj][m][n] = __builtin_amdgcn_mfma_f32_16x16x32_bf16(Bt[n][k], At[m][k], acc[ai][bj][m][n], 0, 0, 0); __builtin_amdgcn_s_setprio(0); } while (0)
; #define PG8_WAIT_V(n) asm volatile("s_waitcnt vmcnt(" #n ")" ::: "memory")
; #define PG8_WAIT_L(n) asm volatile("s_waitcnt lgkmcnt(" #n ")" ::: "memory")
; #define PG8_BAR __builtin_amdgcn_s_barrier()
; #define PG8_SCHED __builtin_amdgcn_sched_barrier(0)
; template <class Epi, class Sched, bool ALIGN_EPI = false, bool SP2 = false>
; __device__ __forceinline__ void gemm_phase(PG8_LAS unsigned char* lds, const Gemm g, const Sched& S, const Epi& E) {
;     ...
;         for (int t = 0; t < nt; t += 2) {
;             const bool last = (t == nt - 2);
;             const char* a1 = cA + (size_t)(t + 1) * kstep;
;             const char* a2 = last ? nA : cA + (size_t)(t + 2) * kstep; const char* b2 = last ? nB : cB + (size_t)(t + 2) * kstep;
;             const char* a3 = a2 + kstep; const char* b3 = b2 + kstep;
;             if (last && has_next) S.a_ready(nxt);
;             if constexpr (SP2) {
;             PG8_LDB(B0, 0, 0); PG8_LDB(B1, 0, 1); PG8_SCHED; PG8_LDA(At, 0, 0); PG8_STAGE(PG8_SA(1, 1), a1 + hstep, voffA);
;             PG8_WAIT_V(8); PG8_WAIT_L(0); PG8_BAR; PG8_MMA(0, 0, At, B0); PG8_MMA(0, 1, At, B1); PG8_BAR; PG8_SCHED;
;             PG8_LDA(At, 0, 1); PG8_STAGE(PG8_SB(0, 0), b2, voffB); PG8_STAGE(PG8_SB(0, 1), b2 + hstep, voffB); PG8_STAGE(PG8_SA(0, 0), a2, voffA);
.LBB0_1988:
	ds_read_b128 v[142:145], v158
	ds_read_b128 v[148:151], v158 offset:1024
	ds_read_b128 v[152:155], v158 offset:2048
	ds_read_b128 v[162:165], v158 offset:3072
	ds_read_b128 v[166:169], v159
	ds_read_b128 v[170:173], v159 offset:1024
	ds_read_b128 v[174:177], v159 offset:2048
	ds_read_b128 v[178:181], v159 offset:3072
	s_add_u32 s36, s34, 0xfff50080
	s_addc_u32 s37, s35, -1
	s_cmp_eq_u32 s71, 40
	s_cselect_b32 s39, s7, s37
	s_cselect_b32 s38, s6, s36
	s_cselect_b32 s37, s31, s70
	s_cselect_b32 s36, s30, s69
	v_lshl_add_u64 v[214:215], s[34:35], 0, v[134:135]
	s_add_i32 m0, s42, 0xc000
	ds_read_b128 v[182:185], v160
	ds_read_b128 v[186:189], v160 offset:1024
	ds_read_b128 v[190:193], v160 offset:2048
	ds_read_b128 v[194:197], v160 offset:3072
	ds_read_b128 v[198:201], v160 offset:4096
	ds_read_b128 v[202:205], v160 offset:5120
	ds_read_b128 v[206:209], v160 offset:6144
	ds_read_b128 v[210:213], v160 offset:7168
	global_load_lds_dwordx4 v[214:215], off
	v_lshl_add_u64 v[214:215], s[34:35], 0, v[136:137]
	s_add_i32 m0, s42, 0xe000
	s_nop 0
	global_load_lds_dwordx4 v[214:215], off
	s_waitcnt vmcnt(8)
	s_waitcnt lgkmcnt(0)
	s_barrier
	s_setprio 1
	s_waitcnt lgkmcnt(0)
	v_mfma_f32_16x16x32_bf16 v[126:129], v[142:145], v[182:185], v[126:129]
	v_mfma_f32_16x16x32_bf16 v[122:125], v[152:155], v[182:185], v[122:125]
	v_mfma_f32_16x16x32_bf16 v[118:121], v[142:145], v[190:193], v[118:121]
	v_mfma_f32_16x16x32_bf16 v[114:117], v[152:155], v[190:193], v[114:117]
	v_mfma_f32_16x16x32_bf16 v[110:113], v[142:145], v[198:201], v[110:113]
	v_mfma_f32_16x16x32_bf16 v[106:109], v[152:155], v[198:201], v[106:109]
	v_mfma_f32_16x16x32_bf16 v[102:105], v[142:145], v[206:209], v[102:105]
	v_mfma_f32_16x16x32_bf16 v[98:101], v[152:155], v[206:209], v[98:101]
	v_mfma_f32_16x16x32_bf16 v[126:129], v[148:151], v[186:189], v[126:129]
	v_mfma_f32_16x16x32_bf16 v[122:125], v[162:165], v[186:189], v[122:125]
	v_mfma_f32_16x16x32_bf16 v[118:121], v[148:151], v[194:197], v[118:121]
	v_mfma_f32_16x16x32_bf16 v[114:117], v[162:165], v[194:197], v[114:117]
	v_mfma_f32_16x16x32_bf16 v[110:113], v[148:151], v[202:205], v[110:113]
	v_mfma_f32_16x16x32_bf16 v[106:109], v[162:165], v[202:205], v[106:109]
	v_mfma_f32_16x16x32_bf16 v[102:105], v[148:151], v[210:213], v[102:105]
	v_mfma_f32_16x16x32_bf16 v[98:101], v[162:165], v[210:213], v[98:101]
	s_setprio 0
	s_setprio 1
	v_mfma_f32_16x16x32_bf16 v[70:73], v[166:169], v[182:185], v[70:73]
	v_mfma_f32_16x16x32_bf16 v[66:69], v[174:177], v[182:185], v[66:69]
	v_mfma_f32_16x16x32_bf16 v[54:57], v[166:169], v[190:193], v[54:57]
	v_mfma_f32_16x16x32_bf16 v[50:53], v[174:177], v[190:193], v[50:53]
	v_mfma_f32_16x16x32_bf16 v[46:49], v[166:169], v[198:201], v[46:49]
	v_mfma_f32_16x16x32_bf16 v[42:45], v[174:177], v[198:201], v[42:45]
	v_mfma_f32_16x16x32_bf16 v[38:41], v[166:169], v[206:209], v[38:41]
	v_mfma_f32_16x16x32_bf16 v[34:37], v[174:177], v[206:209], v[34:37]
	v_mfma_f32_16x16x32_bf16 v[70:73], v[170:173], v[186:189], v[70:73]
	v_mfma_f32_16x16x32_bf16 v[66:69], v[178:181], v[186:189], v[66:69]
	v_mfma_f32_16x16x32_bf16 v[54:57], v[170:173], v[194:197], v[54:57]
	v_mfma_f32_16x16x32_bf16 v[50:53], v[178:181], v[194:197], v[50:53]
	v_mfma_f32_16x16x32_bf16 v[46:49], v[170:173], v[202:205], v[46:49]
	v_mfma_f32_16x16x32_bf16 v[42:45], v[178:181], v[202:205], v[42:45]
	v_mfma_f32_16x16x32_bf16 v[38:41], v[170:173], v[210:213], v[38:41]
	v_mfma_f32_16x16x32_bf16 v[34:37], v[178:181], v[210:213], v[34:37]
	s_setprio 0
	s_barrier
	s_add_i32 s72, s55, s41
	v_lshl_add_u64 v[214:215], s[36:37], 0, v[130:131]
	s_mov_b32 m0, s72
	ds_read_b128 v[182:185], v160 offset:16384
	ds_read_b128 v[186:189], v160 offset:17408
	ds_read_b128 v[190:193], v160 offset:18432
	ds_read_b128 v[194:197], v160 offset:19456
	ds_read_b128 v[198:201], v160 offset:20480
	ds_read_b128 v[202:205], v160 offset:21504
	ds_read_b128 v[206:209], v160 offset:22528
	ds_read_b128 v[210:213], v160 offset:23552
	global_load_lds_dwordx4 v[214:215], off
	s_add_i32 m0, s72, 0x2000
	s_add_u32 s72, s36, 0xb0000
	v_lshl_add_u64 v[216:217], s[36:37], 0, v[132:133]
	s_addc_u32 s73, s37, 0
	s_add_i32 s74, s58, s41
	global_load_lds_dwordx4 v[216:217], off
	v_lshl_add_u64 v[218:219], s[72:73], 0, v[130:131]
	s_mov_b32 m0, s74
	v_lshl_add_u64 v[220:221], s[38:39], 0, v[132:133]
	global_load_lds_dwordx4 v[218:219], off
	v_lshl_add_u64 v[218:219], s[72:73], 0, v[132:133]
	s_add_i32 m0, s74, 0x2000
	s_nop 0
	global_load_lds_dwordx4 v[218:219], off
	v_lshl_add_u64 v[218:219], s[38:39], 0, v[130:131]
	s_mov_b32 m0, s42
	s_nop 0
	global_load_lds_dwordx4 v[218:219], off
	s_mov_b32 m0, s43
	s_nop 0
	global_load_lds_dwordx4 v[220:221], off
	s_waitcnt vmcnt(8)
	s_waitcnt lgkmcnt(0)
	s_barrier
; #define PG8_STAGE(bufoff, gbase, voff) do { _Pragma("unroll") for (int _i = 0; _i < 2; ++_i) \
;         __builtin_amdgcn_global_load_lds((const unsigned*)((const char*)(gbase) + (voff)[_i]), (PG8_LAS unsigned*)(lds + (bufoff) + ldsw + _i * 8192), 16, 0, 0); } while (0)
; #define PG8_LDA(dst, b, h) do { _Pragma("unroll") for (int m = 0; m < 4; ++m) _Pragma("unroll") for (int k = 0; k < 2; ++k) dst[m][k] = *(const PG8_LAS bf16x8*)(lds + PG8_SA(b, h) + aoff + m * 2048 + k * 1024); } while (0)
; #define PG8_LDB(dst, b, h) do { _Pragma("unroll") for (int n = 0; n < 2; ++n) _Pragma("unroll") for (int k = 0; k < 2; ++k) dst[n][k] = *(const PG8_LAS bf16x8*)(lds + PG8_SB(b, h) + boff + n * 2048 + k * 1024); } while (0)
; #define PG8_MMA(ai, bj, At, Bt) do { __builtin_amdgcn_s_setprio(1); _Pragma("unroll") for (int m = 0; m < 4; ++m) _Pragma("unroll") for (int n = 0; n < 2; ++n) _Pragma("unroll") for (int k = 0; k < 2; ++k) \
;         acc[ai][bj][m][n] = __builtin_amdgcn_mfma_f32_16x16x32_bf16(Bt[n][k], At[m][k], acc[ai][bj][m][n], 0, 0, 0); __builtin_amdgcn_s_setprio(0); } while (0)
; #define PG8_WAIT_V(n) asm volatile("s_waitcnt vmcnt(" #n ")" ::: "memory")
; #define PG8_WAIT_L(n) asm volatile("s_waitcnt lgkmcnt(" #n ")" ::: "memory")
; #define PG8_BAR __builtin_amdgcn_s_barrier()
; #define PG8_SCHED __builtin_amdgcn_sched_barrier(0)
; template <class Epi, class Sched, bool ALIGN_EPI = false, bool SP2 = false>
; __device__ __forceinline__ void gemm_phase(PG8_LAS unsigned char* lds, const Gemm g, const Sched& S, const Epi& E) {
;     ...
;             PG8_WAIT_V(8); PG8_WAIT_L(0); PG8_BAR; PG8_MMA(1, 0, At, B0); PG8_MMA(1, 1, At, B1); PG8_BAR; PG8_SCHED;
;             PG8_LDB(B0, 1, 0); PG8_LDB(B1, 1, 1); PG8_SCHED; PG8_LDA(At, 1, 0); PG8_STAGE(PG8_SA(0, 1), a2 + hstep, voffA);
;             PG8_WAIT_V(8); PG8_WAIT_L(0); PG8_BAR; PG8_MMA(0, 0, At, B0); PG8_MMA(0, 1, At, B1); PG8_BAR; PG8_SCHED;
;             PG8_LDA(At, 1, 1); PG8_STAGE(PG8_SB(1, 0), b3, voffB); PG8_STAGE(PG8_SB(1, 1), b3 + hstep, voffB); PG8_STAGE(PG8_SA(1, 0), a3, voffA);
	s_setprio 1
	s_waitcnt lgkmcnt(0)
	v_mfma_f32_16x16x32_bf16 v[94:97], v[142:145], v[182:185], v[94:97]
	v_mfma_f32_16x16x32_bf16 v[90:93], v[152:155], v[182:185], v[90:93]
	v_mfma_f32_16x16x32_bf16 v[86:89], v[142:145], v[190:193], v[86:89]
	v_mfma_f32_16x16x32_bf16 v[82:85], v[152:155], v[190:193], v[82:85]
	v_mfma_f32_16x16x32_bf16 v[78:81], v[142:145], v[198:201], v[78:81]
	v_mfma_f32_16x16x32_bf16 v[74:77], v[152:155], v[198:201], v[74:77]
	v_mfma_f32_16x16x32_bf16 v[62:65], v[142:145], v[206:209], v[62:65]
	v_mfma_f32_16x16x32_bf16 v[58:61], v[152:155], v[206:209], v[58:61]
	v_mfma_f32_16x16x32_bf16 v[94:97], v[148:151], v[186:189], v[94:97]
	v_mfma_f32_16x16x32_bf16 v[90:93], v[162:165], v[186:189], v[90:93]
	v_mfma_f32_16x16x32_bf16 v[86:89], v[148:151], v[194:197], v[86:89]
	v_mfma_f32_16x16x32_bf16 v[82:85], v[162:165], v[194:197], v[82:85]
	v_mfma_f32_16x16x32_bf16 v[78:81], v[148:151], v[202:205], v[78:81]
	v_mfma_f32_16x16x32_bf16 v[74:77], v[162:165], v[202:205], v[74:77]
	v_mfma_f32_16x16x32_bf16 v[62:65], v[148:151], v[210:213], v[62:65]
	v_mfma_f32_16x16x32_bf16 v[58:61], v[162:165], v[210:213], v[58:61]
	s_setprio 0
	s_setprio 1
	v_mfma_f32_16x16x32_bf16 v[30:33], v[166:169], v[182:185], v[30:33]
	v_mfma_f32_16x16x32_bf16 v[26:29], v[174:177], v[182:185], v[26:29]
	v_mfma_f32_16x16x32_bf16 v[22:25], v[166:169], v[190:193], v[22:25]
	v_mfma_f32_16x16x32_bf16 v[18:21], v[174:177], v[190:193], v[18:21]
	v_mfma_f32_16x16x32_bf16 v[14:17], v[166:169], v[198:201], v[14:17]
	v_mfma_f32_16x16x32_bf16 v[10:13], v[174:177], v[198:201], v[10:13]
	v_mfma_f32_16x16x32_bf16 v[6:9], v[166:169], v[206:209], v[6:9]
	v_mfma_f32_16x16x32_bf16 v[2:5], v[174:177], v[206:209], v[2:5]
	v_mfma_f32_16x16x32_bf16 v[30:33], v[170:173], v[186:189], v[30:33]
	v_mfma_f32_16x16x32_bf16 v[26:29], v[178:181], v[186:189], v[26:29]
	v_mfma_f32_16x16x32_bf16 v[22:25], v[170:173], v[194:197], v[22:25]
	v_mfma_f32_16x16x32_bf16 v[18:21], v[178:181], v[194:197], v[18:21]
	v_mfma_f32_16x16x32_bf16 v[14:17], v[170:173], v[202:205], v[14:17]
	v_mfma_f32_16x16x32_bf16 v[10:13], v[178:181], v[202:205], v[10:13]
	v_mfma_f32_16x16x32_bf16 v[6:9], v[170:173], v[210:213], v[6:9]
	v_mfma_f32_16x16x32_bf16 v[2:5], v[178:181], v[210:213], v[2:5]
	s_setprio 0
	s_barrier
	s_add_i32 s72, 0, 0x18000
	v_add_u32_e32 v161, s72, v157
	s_add_i32 s73, 0, 0x1c000
	ds_read_b128 v[142:145], v161
	ds_read_b128 v[148:151], v161 offset:1024
	ds_read_b128 v[152:155], v161 offset:2048
	ds_read_b128 v[162:165], v161 offset:3072
	v_add_u32_e32 v161, s73, v157
	ds_read_b128 v[166:169], v161
	ds_read_b128 v[170:173], v161 offset:1024
	ds_read_b128 v[174:177], v161 offset:2048
	ds_read_b128 v[178:181], v161 offset:3072
	s_add_u32 s38, s38, 0xb0000
	s_addc_u32 s39, s39, 0
	s_mov_b32 m0, s44
	v_lshl_add_u64 v[222:223], s[38:39], 0, v[130:131]
	ds_read_b128 v[182:185], v160 offset:32768
	ds_read_b128 v[186:189], v160 offset:33792
	ds_read_b128 v[190:193], v160 offset:34816
	ds_read_b128 v[194:197], v160 offset:35840
	ds_read_b128 v[198:201], v160 offset:36864
	ds_read_b128 v[202:205], v160 offset:37888
	ds_read_b128 v[206:209], v160 offset:38912
	ds_read_b128 v[210:213], v160 offset:39936
	global_load_lds_dwordx4 v[222:223], off
	v_lshl_add_u64 v[222:223], s[38:39], 0, v[132:133]
	s_mov_b32 m0, s45
	s_nop 0
	global_load_lds_dwordx4 v[222:223], off
	s_waitcnt vmcnt(8)
	s_waitcnt lgkmcnt(0)
	s_barrier
	s_setprio 1
	s_waitcnt lgkmcnt(0)
	v_mfma_f32_16x16x32_bf16 v[126:129], v[142:145], v[182:185], v[126:129]
	v_mfma_f32_16x16x32_bf16 v[122:125], v[152:155], v[182:185], v[122:125]
	v_mfma_f32_16x16x32_bf16 v[118:121], v[142:145], v[190:193], v[118:121]
	v_mfma_f32_16x16x32_bf16 v[114:117], v[152:155], v[190:193], v[114:117]
	v_mfma_f32_16x16x32_bf16 v[110:113], v[142:145], v[198:201], v[110:113]
	v_mfma_f32_16x16x32_bf16 v[106:109], v[152:155], v[198:201], v[106:109]
	v_mfma_f32_16x16x32_bf16 v[102:105], v[142:145], v[206:209], v[102:105]
	v_mfma_f32_16x16x32_bf16 v[98:101], v[152:155], v[206:209], v[98:101]
	v_mfma_f32_16x16x32_bf16 v[126:129], v[148:151], v[186:189], v[126:129]
	v_mfma_f32_16x16x32_bf16 v[122:125], v[162:165], v[186:189], v[122:125]
	v_mfma_f32_16x16x32_bf16 v[118:121], v[148:151], v[194:197], v[118:121]
	v_mfma_f32_16x16x32_bf16 v[114:117], v[162:165], v[194:197], v[114:117]
	v_mfma_f32_16x16x32_bf16 v[110:113], v[148:151], v[202:205], v[110:113]
	v_mfma_f32_16x16x32_bf16 v[106:109], v[162:165], v[202:205], v[106:109]
	v_mfma_f32_16x16x32_bf16 v[102:105], v[148:151], v[210:213], v[102:105]
	v_mfma_f32_16x16x32_bf16 v[98:101], v[162:165], v[210:213], v[98:101]
	s_setprio 0
	s_setprio 1
	v_mfma_f32_16x16x32_bf16 v[70:73], v[166:169], v[182:185], v[70:73]
	v_mfma_f32_16x16x32_bf16 v[66:69], v[174:177], v[182:185], v[66:69]
	v_mfma_f32_16x16x32_bf16 v[54:57], v[166:169], v[190:193], v[54:57]
	v_mfma_f32_16x16x32_bf16 v[50:53], v[174:177], v[190:193], v[50:53]
	v_mfma_f32_16x16x32_bf16 v[46:49], v[166:169], v[198:201], v[46:49]
	v_mfma_f32_16x16x32_bf16 v[42:45], v[174:177], v[198:201], v[42:45]
	v_mfma_f32_16x16x32_bf16 v[38:41], v[166:169], v[206:209], v[38:41]
	v_mfma_f32_16x16x32_bf16 v[34:37], v[174:177], v[206:209], v[34:37]
	v_mfma_f32_16x16x32_bf16 v[70:73], v[170:173], v[186:189], v[70:73]
	v_mfma_f32_16x16x32_bf16 v[66:69], v[178:181], v[186:189], v[66:69]
	v_mfma_f32_16x16x32_bf16 v[54:57], v[170:173], v[194:197], v[54:57]
	v_mfma_f32_16x16x32_bf16 v[50:53], v[178:181], v[194:197], v[50:53]
	v_mfma_f32_16x16x32_bf16 v[46:49], v[170:173], v[202:205], v[46:49]
	v_mfma_f32_16x16x32_bf16 v[42:45], v[178:181], v[202:205], v[42:45]
	v_mfma_f32_16x16x32_bf16 v[38:41], v[170:173], v[210:213], v[38:41]
	v_mfma_f32_16x16x32_bf16 v[34:37], v[178:181], v[210:213], v[34:37]
	s_setprio 0
	s_barrier
; #define PG8_STAGE(bufoff, gbase, voff) do { _Pragma("unroll") for (int _i = 0; _i < 2; ++_i) \
;         __builtin_amdgcn_global_load_lds((const unsigned*)((const char*)(gbase) + (voff)[_i]), (PG8_LAS unsigned*)(lds + (bufoff) + ldsw + _i * 8192), 16, 0, 0); } while (0)
; #define PG8_LDA(dst, b, h) do { _Pragma("unroll") for (int m = 0; m < 4; ++m) _Pragma("unroll") for (int k = 0; k < 2; ++k) dst[m][k] = *(const PG8_LAS bf16x8*)(lds + PG8_SA(b, h) + aoff + m * 2048 + k * 1024); } while (0)
; #define PG8_MMA(ai, bj, At, Bt) do { __builtin_amdgcn_s_setprio(1); _Pragma("unroll") for (int m = 0; m < 4; ++m) _Pragma("unroll") for (int n = 0; n < 2; ++n) _Pragma("unroll") for (int k = 0; k < 2; ++k) \
;         acc[ai][bj][m][n] = __builtin_amdgcn_mfma_f32_16x16x32_bf16(Bt[n][k], At[m][k], acc[ai][bj][m][n], 0, 0, 0); __builtin_amdgcn_s_setprio(0); } while (0)
; #define PG8_WAIT_V(n) asm volatile("s_waitcnt vmcnt(" #n ")" ::: "memory")
; #define PG8_WAIT_L(n) asm volatile("s_waitcnt lgkmcnt(" #n ")" ::: "memory")
; #define PG8_BAR __builtin_amdgcn_s_barrier()
; #define PG8_SCHED __builtin_amdgcn_sched_barrier(0)
; template <class Epi, class Sched, bool ALIGN_EPI = false, bool SP2 = false>
; __device__ __forceinline__ void gemm_phase(PG8_LAS unsigned char* lds, const Gemm g, const Sched& S, const Epi& E) {
;     ...
;         for (int t = 0; t < nt; t += 2) {
;     ...
;             PG8_LDA(At, 1, 1); PG8_STAGE(PG8_SB(1, 0), b3, voffB); PG8_STAGE(PG8_SB(1, 1), b3 + hstep, voffB); PG8_STAGE(PG8_SA(1, 0), a3, voffA);
;             PG8_WAIT_V(8); PG8_WAIT_L(0); PG8_BAR; PG8_MMA(1, 0, At, B0); PG8_MMA(1, 1, At, B1); PG8_BAR; PG8_SCHED;
	s_add_i32 s38, s72, s41
	v_lshl_add_u64 v[214:215], v[214:215], 0, s[12:13]
	s_mov_b32 m0, s38
	ds_read_b128 v[182:185], v160 offset:49152
	ds_read_b128 v[186:189], v160 offset:50176
	ds_read_b128 v[190:193], v160 offset:51200
	ds_read_b128 v[194:197], v160 offset:52224
	ds_read_b128 v[198:201], v160 offset:53248
	ds_read_b128 v[202:205], v160 offset:54272
	ds_read_b128 v[206:209], v160 offset:55296
	ds_read_b128 v[210:213], v160 offset:56320
	global_load_lds_dwordx4 v[214:215], off
	s_add_i32 m0, s38, 0x2000
	s_add_u32 s36, s36, 0xb0080
	v_lshl_add_u64 v[214:215], v[216:217], 0, s[12:13]
	s_addc_u32 s37, s37, 0
	s_add_i32 s38, s73, s41
	global_load_lds_dwordx4 v[214:215], off
	v_lshl_add_u64 v[214:215], s[36:37], 0, v[130:131]
	s_mov_b32 m0, s38
	s_nop 0
	global_load_lds_dwordx4 v[214:215], off
	v_lshl_add_u64 v[214:215], s[36:37], 0, v[132:133]
	s_add_i32 m0, s38, 0x2000
	s_nop 0
	global_load_lds_dwordx4 v[214:215], off
	v_lshl_add_u64 v[214:215], v[218:219], 0, s[12:13]
	s_mov_b32 m0, s51
	s_nop 0
	global_load_lds_dwordx4 v[214:215], off
	v_lshl_add_u64 v[214:215], v[220:221], 0, s[12:13]
	s_mov_b32 m0, s52
	s_nop 0
	global_load_lds_dwordx4 v[214:215], off
	s_waitcnt vmcnt(8)
	s_waitcnt lgkmcnt(0)
	s_barrier
	s_setprio 1
	s_waitcnt lgkmcnt(0)
	v_mfma_f32_16x16x32_bf16 v[94:97], v[142:145], v[182:185], v[94:97]
	v_mfma_f32_16x16x32_bf16 v[90:93], v[152:155], v[182:185], v[90:93]
	v_mfma_f32_16x16x32_bf16 v[86:89], v[142:145], v[190:193], v[86:89]
	v_mfma_f32_16x16x32_bf16 v[82:85], v[152:155], v[190:193], v[82:85]
	v_mfma_f32_16x16x32_bf16 v[78:81], v[142:145], v[198:201], v[78:81]
	v_mfma_f32_16x16x32_bf16 v[74:77], v[152:155], v[198:201], v[74:77]
	v_mfma_f32_16x16x32_bf16 v[62:65], v[142:145], v[206:209], v[62:65]
	v_mfma_f32_16x16x32_bf16 v[58:61], v[152:155], v[206:209], v[58:61]
	v_mfma_f32_16x16x32_bf16 v[94:97], v[148:151], v[186:189], v[94:97]
	v_mfma_f32_16x16x32_bf16 v[90:93], v[162:165], v[186:189], v[90:93]
	v_mfma_f32_16x16x32_bf16 v[86:89], v[148:151], v[194:197], v[86:89]
	v_mfma_f32_16x16x32_bf16 v[82:85], v[162:165], v[194:197], v[82:85]
	v_mfma_f32_16x16x32_bf16 v[78:81], v[148:151], v[202:205], v[78:81]
	v_mfma_f32_16x16x32_bf16 v[74:77], v[162:165], v[202:205], v[74:77]
	v_mfma_f32_16x16x32_bf16 v[62:65], v[148:151], v[210:213], v[62:65]
	v_mfma_f32_16x16x32_bf16 v[58:61], v[162:165], v[210:213], v[58:61]
	s_setprio 0
	s_setprio 1
	v_mfma_f32_16x16x32_bf16 v[30:33], v[166:169], v[182:185], v[30:33]
	v_mfma_f32_16x16x32_bf16 v[26:29], v[174:177], v[182:185], v[26:29]
	v_mfma_f32_16x16x32_bf16 v[22:25], v[166:169], v[190:193], v[22:25]
	v_mfma_f32_16x16x32_bf16 v[18:21], v[174:177], v[190:193], v[18:21]
	v_mfma_f32_16x16x32_bf16 v[14:17], v[166:169], v[198:201], v[14:17]
	v_mfma_f32_16x16x32_bf16 v[10:13], v[174:177], v[198:201], v[10:13]
	v_mfma_f32_16x16x32_bf16 v[6:9], v[166:169], v[206:209], v[6:9]
	v_mfma_f32_16x16x32_bf16 v[2:5], v[174:177], v[206:209], v[2:5]
	v_mfma_f32_16x16x32_bf16 v[30:33], v[170:173], v[186:189], v[30:33]
	v_mfma_f32_16x16x32_bf16 v[26:29], v[178:181], v[186:189], v[26:29]
	v_mfma_f32_16x16x32_bf16 v[22:25], v[170:173], v[194:197], v[22:25]
	v_mfma_f32_16x16x32_bf16 v[18:21], v[178:181], v[194:197], v[18:21]
	v_mfma_f32_16x16x32_bf16 v[14:17], v[170:173], v[202:205], v[14:17]
	v_mfma_f32_16x16x32_bf16 v[10:13], v[178:181], v[202:205], v[10:13]
	v_mfma_f32_16x16x32_bf16 v[6:9], v[170:173], v[210:213], v[6:9]
	v_mfma_f32_16x16x32_bf16 v[2:5], v[178:181], v[210:213], v[2:5]
	s_setprio 0
	s_add_i32 s71, s71, 2
	s_add_u32 s34, s34, 0x100
	s_addc_u32 s35, s35, 0
	s_add_u32 s69, s69, 0x100
	s_addc_u32 s70, s70, 0
	s_cmp_gt_u32 s71, 41
	s_barrier
	s_cbranch_scc0 .LBB0_1988
	s_and_b64 vcc, exec, s[14:15]
	s_cbranch_vccz .LBB0_1991
	s_barrier
